# combo11 + prologue weight-transpose items load all 32 dwords of a tile before the first LDS write (the two 16-load batches were drained one after the other)
# speedup vs baseline: 1.0031x; 1.0031x over previous
; #define LAS __attribute__((address_space(3)))
; __device__ __forceinline__ void transpose_item(const float* W, size_t ldw, bf16* WT, size_t K, LAS float* scr, int lane) {
; #pragma unroll 8
;     for (int i = 0; i < 32; ++i) { const int kk = 2 * i + (lane >> 5); scr[kk * 33 + (lane & 31)] = W[(size_t)kk * ldw + (lane & 31)]; }
.LBB0_28:
	s_lshl_b32 s23, s9, 1
	s_lshl_b32 s25, s10, 1
	v_or_b32_e32 v22, s25, v18
	s_add_i32 s28, s23, 4
	s_add_i32 s29, s25, 4
	v_mov_b32_e32 v7, v23
	s_add_i32 s31, s25, 8
	v_lshlrev_b64 v[52:53], 13, v[22:23]
	v_mad_u64_u32 v[54:55], s[26:27], v22, s14, v[24:25]
	v_or_b32_e32 v6, s28, v1
	v_or_b32_e32 v22, s29, v18
	v_mov_b32_e32 v5, v23
	v_or_b32_e32 v4, s23, v1
	s_add_i32 s34, s25, 12
	v_lshlrev_b64 v[56:57], 13, v[6:7]
	v_lshlrev_b64 v[58:59], 13, v[22:23]
	v_mad_u64_u32 v[60:61], s[26:27], v22, s14, v[24:25]
	v_or_b32_e32 v22, s31, v18
	s_add_i32 s30, s23, 8
	s_add_i32 s33, s23, 12
	s_add_i32 s36, s25, 16
	v_lshlrev_b64 v[50:51], 13, v[4:5]
	v_lshl_add_u64 v[52:53], v[2:3], 0, v[52:53]
	v_lshl_add_u64 v[56:57], v[2:3], 0, v[56:57]
	v_lshlrev_b64 v[74:75], 13, v[22:23]
	v_mad_u64_u32 v[76:77], s[26:27], v22, s14, v[24:25]
	v_or_b32_e32 v22, s34, v18
	v_mov_b32_e32 v9, v23
	v_mov_b32_e32 v11, v23
	s_add_i32 s35, s23, 16
	s_add_i32 s38, s25, 20
	v_or_b32_e32 v8, s30, v1
	v_or_b32_e32 v10, s33, v1
	v_lshl_add_u64 v[50:51], v[2:3], 0, v[50:51]
	v_lshl_add_u64 v[58:59], v[2:3], 0, v[58:59]
	global_load_dword v37, v[52:53], off
	global_load_dword v39, v[50:51], off
	global_load_dword v41, v[58:59], off
	global_load_dword v43, v[56:57], off
	v_lshlrev_b64 v[52:53], 13, v[22:23]
	v_mad_u64_u32 v[56:57], s[26:27], v22, s14, v[24:25]
	v_or_b32_e32 v22, s36, v18
	v_mov_b32_e32 v13, v23
	s_add_i32 s37, s23, 20
	s_add_i32 s40, s25, 24
	v_or_b32_e32 v12, s35, v1
	v_lshlrev_b64 v[62:63], 13, v[8:9]
	v_lshlrev_b64 v[64:65], 13, v[10:11]
	v_lshl_add_u64 v[50:51], v[2:3], 0, v[74:75]
	v_lshl_add_u64 v[52:53], v[2:3], 0, v[52:53]
	v_lshlrev_b64 v[58:59], 13, v[22:23]
	v_mad_u64_u32 v[74:75], s[26:27], v22, s14, v[24:25]
	v_or_b32_e32 v22, s38, v18
	v_mov_b32_e32 v15, v23
	s_add_i32 s25, s25, 28
	v_or_b32_e32 v14, s37, v1
	v_lshlrev_b64 v[66:67], 13, v[12:13]
	v_lshl_add_u64 v[62:63], v[2:3], 0, v[62:63]
	v_lshl_add_u64 v[64:65], v[2:3], 0, v[64:65]
	global_load_dword v45, v[50:51], off
	global_load_dword v49, v[62:63], off
	global_load_dword v55, v[52:53], off
	global_load_dword v57, v[64:65], off
	v_lshl_add_u64 v[50:51], v[2:3], 0, v[58:59]
	v_lshlrev_b64 v[52:53], 13, v[22:23]
	v_mad_u64_u32 v[58:59], s[26:27], v22, s14, v[24:25]
	v_or_b32_e32 v22, s40, v18
	s_add_i32 s39, s23, 24
	s_add_i32 s23, s23, 28
	v_lshlrev_b64 v[68:69], 13, v[14:15]
	v_lshl_add_u64 v[66:67], v[2:3], 0, v[66:67]
	v_lshl_add_u64 v[52:53], v[2:3], 0, v[52:53]
	v_lshlrev_b64 v[62:63], 13, v[22:23]
	v_mad_u64_u32 v[64:65], s[26:27], v22, s14, v[24:25]
	v_or_b32_e32 v22, s25, v18
	v_mov_b32_e32 v17, v23
	v_mov_b32_e32 v47, v23
	v_or_b32_e32 v16, s39, v1
	v_or_b32_e32 v46, s23, v1
	v_lshl_add_u64 v[68:69], v[2:3], 0, v[68:69]
	global_load_dword v59, v[50:51], off
	global_load_dword v61, v[66:67], off
	global_load_dword v65, v[52:53], off
	s_nop 0
	global_load_dword v66, v[68:69], off
	v_lshlrev_b64 v[52:53], 13, v[22:23]
	v_lshlrev_b64 v[70:71], 13, v[16:17]
	v_lshlrev_b64 v[72:73], 13, v[46:47]
	v_lshl_add_u64 v[50:51], v[2:3], 0, v[62:63]
	v_lshl_add_u64 v[52:53], v[2:3], 0, v[52:53]
	v_lshl_add_u64 v[70:71], v[2:3], 0, v[70:71]
	v_lshl_add_u64 v[72:73], v[2:3], 0, v[72:73]
	global_load_dword v62, v[50:51], off
	global_load_dword v63, v[70:71], off
	s_nop 0
	global_load_dword v52, v[52:53], off
	s_nop 0
	global_load_dword v53, v[72:73], off
	s_add_i32 s10, s10, 16
	s_add_i32 s9, s9, 16
	s_add_i32 s11, s11, -16
	s_cmp_lg_u32 s11, 0
	v_mad_u64_u32 v[4:5], s[26:27], v4, s14, v[24:25]
	v_mad_u64_u32 v[6:7], s[26:27], v6, s14, v[24:25]
	v_mad_u64_u32 v[8:9], s[26:27], v8, s14, v[24:25]
	v_mad_u64_u32 v[10:11], s[26:27], v10, s14, v[24:25]
	v_mad_u64_u32 v[12:13], s[26:27], v12, s14, v[24:25]
	v_mad_u64_u32 v[14:15], s[26:27], v14, s14, v[24:25]
	v_mad_u64_u32 v[16:17], s[26:27], v16, s14, v[24:25]
	v_mad_u64_u32 v[46:47], s[26:27], v46, s14, v[24:25]
	v_mad_u64_u32 v[50:51], s[26:27], v22, s14, v[24:25]
	v_mov_b32_e32 v119, v23
	s_lshl_b32 s23, s9, 1
	s_lshl_b32 s25, s10, 1
	v_or_b32_e32 v118, s25, v18
	s_add_i32 s28, s23, 4
	s_add_i32 s29, s25, 4
	v_mov_b32_e32 v103, v119
	s_add_i32 s31, s25, 8
	v_lshlrev_b64 v[148:149], 13, v[118:119]
	v_mad_u64_u32 v[150:151], s[26:27], v118, s14, v[24:25]
	v_or_b32_e32 v102, s28, v1
	v_or_b32_e32 v118, s29, v18
	v_mov_b32_e32 v101, v119
	v_or_b32_e32 v100, s23, v1
	s_add_i32 s34, s25, 12
	v_lshlrev_b64 v[152:153], 13, v[102:103]
	v_lshlrev_b64 v[154:155], 13, v[118:119]
	v_mad_u64_u32 v[156:157], s[26:27], v118, s14, v[24:25]
	v_or_b32_e32 v118, s31, v18
	s_add_i32 s30, s23, 8
	s_add_i32 s33, s23, 12
	s_add_i32 s36, s25, 16
	v_lshlrev_b64 v[146:147], 13, v[100:101]
	v_lshl_add_u64 v[148:149], v[2:3], 0, v[148:149]
	v_lshl_add_u64 v[152:153], v[2:3], 0, v[152:153]
	v_lshlrev_b64 v[170:171], 13, v[118:119]
	v_mad_u64_u32 v[172:173], s[26:27], v118, s14, v[24:25]
	v_or_b32_e32 v118, s34, v18
	v_mov_b32_e32 v105, v119
	v_mov_b32_e32 v107, v119
	s_add_i32 s35, s23, 16
	s_add_i32 s38, s25, 20
	v_or_b32_e32 v104, s30, v1
	v_or_b32_e32 v106, s33, v1
	v_lshl_add_u64 v[146:147], v[2:3], 0, v[146:147]
	v_lshl_add_u64 v[154:155], v[2:3], 0, v[154:155]
	global_load_dword v133, v[148:149], off
	global_load_dword v135, v[146:147], off
	global_load_dword v137, v[154:155], off
	global_load_dword v139, v[152:153], off
	v_lshlrev_b64 v[148:149], 13, v[118:119]
	v_mad_u64_u32 v[152:153], s[26:27], v118, s14, v[24:25]
	v_or_b32_e32 v118, s36, v18
	v_mov_b32_e32 v109, v119
	s_add_i32 s37, s23, 20
	s_add_i32 s40, s25, 24
	v_or_b32_e32 v108, s35, v1
	v_lshlrev_b64 v[158:159], 13, v[104:105]
	v_lshlrev_b64 v[160:161], 13, v[106:107]
	v_lshl_add_u64 v[146:147], v[2:3], 0, v[170:171]
; #define LAS __attribute__((address_space(3)))
; __device__ __forceinline__ unsigned cvt_pk_bf16(float lo, float hi) { unsigned r; asm volatile("v_cvt_pk_bf16_f32 %0, %1, %2" : "=v"(r) : "v"(lo), "v"(hi)); return r; }
; __device__ __forceinline__ void transpose_item(const float* W, size_t ldw, bf16* WT, size_t K, LAS float* scr, int lane) {
;     ...
;     for (int i = 0; i < 32; ++i) { const int kk = 2 * i + (lane >> 5); scr[kk * 33 + (lane & 31)] = W[(size_t)kk * ldw + (lane & 31)]; }
;     asm volatile("s_waitcnt lgkmcnt(0)" ::: "memory");
;     const int c = lane & 7;
; #pragma unroll
;     for (int j = 0; j < 4; ++j) { const int n = (lane >> 3) + 8 * j; const LAS float* s = scr + (8 * c) * 33 + n;
;         u32x4 o; o.x = cvt_pk_bf16(s[0 * 33], s[1 * 33]); o.y = cvt_pk_bf16(s[2 * 33], s[3 * 33]); o.z = cvt_pk_bf16(s[4 * 33], s[5 * 33]); o.w = cvt_pk_bf16(s[6 * 33], s[7 * 33]);
;         *(u32x4*)(WT + (size_t)n * K + 8 * c) = o; }
; __device__ __forceinline__ void phase_prologue(const In& in, unsigned char* ws, LAS unsigned char* lds, int tid, int wave, int lane) {
;     ...
;         if (r < I_O) {
;             const int nblk = D / 32, kb = r / nblk, nb = r % nblk, n0 = nb * 32, k0 = kb * 64;
;             const float* W = in.w_out + ((size_t)l * D + k0) * D + n0;
;             bf16* WT = (bf16*)(ws + WS_WO + (size_t)l * SZ_WO) + (size_t)n0 * D + k0;
;             transpose_item(W, D, WT, D, scr, lane);
	v_lshl_add_u64 v[148:149], v[2:3], 0, v[148:149]
	v_lshlrev_b64 v[154:155], 13, v[118:119]
	v_mad_u64_u32 v[170:171], s[26:27], v118, s14, v[24:25]
	v_or_b32_e32 v118, s38, v18
	v_mov_b32_e32 v111, v119
	s_add_i32 s25, s25, 28
	v_or_b32_e32 v110, s37, v1
	v_lshlrev_b64 v[162:163], 13, v[108:109]
	v_lshl_add_u64 v[158:159], v[2:3], 0, v[158:159]
	v_lshl_add_u64 v[160:161], v[2:3], 0, v[160:161]
	global_load_dword v141, v[146:147], off
	global_load_dword v145, v[158:159], off
	global_load_dword v151, v[148:149], off
	global_load_dword v153, v[160:161], off
	v_lshl_add_u64 v[146:147], v[2:3], 0, v[154:155]
	v_lshlrev_b64 v[148:149], 13, v[118:119]
	v_mad_u64_u32 v[154:155], s[26:27], v118, s14, v[24:25]
	v_or_b32_e32 v118, s40, v18
	s_add_i32 s39, s23, 24
	s_add_i32 s23, s23, 28
	v_lshlrev_b64 v[164:165], 13, v[110:111]
	v_lshl_add_u64 v[162:163], v[2:3], 0, v[162:163]
	v_lshl_add_u64 v[148:149], v[2:3], 0, v[148:149]
	v_lshlrev_b64 v[158:159], 13, v[118:119]
	v_mad_u64_u32 v[160:161], s[26:27], v118, s14, v[24:25]
	v_or_b32_e32 v118, s25, v18
	v_mov_b32_e32 v113, v119
	v_mov_b32_e32 v143, v119
	v_or_b32_e32 v112, s39, v1
	v_or_b32_e32 v142, s23, v1
	v_lshl_add_u64 v[164:165], v[2:3], 0, v[164:165]
	global_load_dword v155, v[146:147], off
	global_load_dword v157, v[162:163], off
	global_load_dword v161, v[148:149], off
	s_nop 0
	global_load_dword v162, v[164:165], off
	v_lshlrev_b64 v[148:149], 13, v[118:119]
	v_lshlrev_b64 v[166:167], 13, v[112:113]
	v_lshlrev_b64 v[168:169], 13, v[142:143]
	v_lshl_add_u64 v[146:147], v[2:3], 0, v[158:159]
	v_lshl_add_u64 v[148:149], v[2:3], 0, v[148:149]
	v_lshl_add_u64 v[166:167], v[2:3], 0, v[166:167]
	v_lshl_add_u64 v[168:169], v[2:3], 0, v[168:169]
	global_load_dword v158, v[146:147], off
	global_load_dword v159, v[166:167], off
	s_nop 0
	global_load_dword v148, v[148:149], off
	s_nop 0
	global_load_dword v149, v[168:169], off
	s_add_i32 s10, s10, 16
	s_add_i32 s9, s9, 16
	s_add_i32 s11, s11, -16
	s_cmp_lg_u32 s11, 0
	v_mad_u64_u32 v[100:101], s[26:27], v100, s14, v[24:25]
	v_mad_u64_u32 v[102:103], s[26:27], v102, s14, v[24:25]
	v_mad_u64_u32 v[104:105], s[26:27], v104, s14, v[24:25]
	v_mad_u64_u32 v[106:107], s[26:27], v106, s14, v[24:25]
	v_mad_u64_u32 v[108:109], s[26:27], v108, s14, v[24:25]
	v_mad_u64_u32 v[110:111], s[26:27], v110, s14, v[24:25]
	v_mad_u64_u32 v[112:113], s[26:27], v112, s14, v[24:25]
	v_mad_u64_u32 v[142:143], s[26:27], v142, s14, v[24:25]
	v_mad_u64_u32 v[146:147], s[26:27], v118, s14, v[24:25]
	s_waitcnt vmcnt(31)
	ds_write_b32 v54, v37
	s_waitcnt vmcnt(30)
	ds_write_b32 v4, v39
	s_waitcnt vmcnt(29)
	ds_write_b32 v60, v41
	s_waitcnt vmcnt(28)
	ds_write_b32 v6, v43
	s_waitcnt vmcnt(27)
	ds_write_b32 v76, v45
	s_waitcnt vmcnt(26)
	ds_write_b32 v8, v49
	s_waitcnt vmcnt(25)
	ds_write_b32 v56, v55
	s_waitcnt vmcnt(24)
	ds_write_b32 v10, v57
	s_waitcnt vmcnt(23)
	ds_write_b32 v74, v59
	s_waitcnt vmcnt(22)
	ds_write_b32 v12, v61
	s_waitcnt vmcnt(21)
	ds_write_b32 v58, v65
	s_waitcnt vmcnt(20)
	ds_write_b32 v14, v66
	s_waitcnt vmcnt(19)
	ds_write_b32 v64, v62
	s_waitcnt vmcnt(18)
	ds_write_b32 v16, v63
	s_waitcnt vmcnt(17)
	ds_write_b32 v50, v52
	s_waitcnt vmcnt(16)
	ds_write_b32 v46, v53
	s_waitcnt vmcnt(15)
	ds_write_b32 v150, v133
	s_waitcnt vmcnt(14)
	ds_write_b32 v100, v135
	s_waitcnt vmcnt(13)
	ds_write_b32 v156, v137
	s_waitcnt vmcnt(12)
	ds_write_b32 v102, v139
	s_waitcnt vmcnt(11)
	ds_write_b32 v172, v141
	s_waitcnt vmcnt(10)
	ds_write_b32 v104, v145
	s_waitcnt vmcnt(9)
	ds_write_b32 v152, v151
	s_waitcnt vmcnt(8)
	ds_write_b32 v106, v153
	s_waitcnt vmcnt(7)
	ds_write_b32 v170, v155
	s_waitcnt vmcnt(6)
	ds_write_b32 v108, v157
	s_waitcnt vmcnt(5)
	ds_write_b32 v154, v161
	s_waitcnt vmcnt(4)
	ds_write_b32 v110, v162
	s_waitcnt vmcnt(3)
	ds_write_b32 v160, v158
	s_waitcnt vmcnt(2)
	ds_write_b32 v112, v159
	s_waitcnt vmcnt(1)
	ds_write_b32 v146, v148
	s_waitcnt vmcnt(0)
	ds_write_b32 v142, v149
	s_lshl_b64 s[10:11], s[6:7], 23
	s_lshl_b32 s7, s8, 12
	v_readlane_b32 s2, v252, 53
	s_add_u32 s8, s2, s10
	v_readlane_b32 s2, v252, 54
	s_addc_u32 s9, s2, s11
	s_add_u32 s7, s8, s7
	s_waitcnt lgkmcnt(0)
	s_addc_u32 s10, s9, 0
	s_lshl_b64 s[8:9], s[0:1], 1
	ds_read2_b32 v[2:3], v21 offset1:33
	s_add_u32 s8, s7, s8
	s_waitcnt lgkmcnt(0)
	v_cvt_pk_bf16_f32 v2, v2, v3
	ds_read2_b32 v[4:5], v21 offset0:66 offset1:99
	v_lshlrev_b32_e32 v22, 1, v26
	s_addc_u32 s9, s10, s9
	s_waitcnt lgkmcnt(0)
	v_cvt_pk_bf16_f32 v3, v4, v5
	ds_read2_b32 v[4:5], v21 offset0:132 offset1:165
	v_lshl_add_u64 v[8:9], s[8:9], 0, v[22:23]
	v_lshlrev_b32_e32 v22, 1, v28
	s_waitcnt lgkmcnt(0)
	v_cvt_pk_bf16_f32 v4, v4, v5
	ds_read2_b32 v[6:7], v21 offset0:198 offset1:231
	s_waitcnt lgkmcnt(0)
	v_cvt_pk_bf16_f32 v5, v6, v7
	v_lshl_add_u64 v[10:11], v[8:9], 0, v[22:23]
	ds_read2_b32 v[6:7], v21 offset0:8 offset1:41
	global_store_dwordx4 v[10:11], v[2:5], off
	v_lshlrev_b32_e32 v22, 1, v30
	v_lshl_add_u64 v[10:11], v[8:9], 0, v[22:23]
	s_waitcnt lgkmcnt(0)
	v_cvt_pk_bf16_f32 v2, v6, v7
	ds_read2_b32 v[4:5], v21 offset0:74 offset1:107
	s_waitcnt lgkmcnt(0)
	v_cvt_pk_bf16_f32 v3, v4, v5
	ds_read2_b32 v[4:5], v21 offset0:140 offset1:173
	s_waitcnt lgkmcnt(0)
	v_cvt_pk_bf16_f32 v4, v4, v5
	ds_read2_b32 v[6:7], v21 offset0:206 offset1:239
	s_waitcnt lgkmcnt(0)
	v_cvt_pk_bf16_f32 v5, v6, v7
	ds_read2_b32 v[6:7], v21 offset0:16 offset1:49
	global_store_dwordx4 v[10:11], v[2:5], off
	v_lshlrev_b32_e32 v22, 1, v32
	v_lshl_add_u64 v[10:11], v[8:9], 0, v[22:23]
	s_waitcnt lgkmcnt(0)
	v_cvt_pk_bf16_f32 v2, v6, v7
	ds_read2_b32 v[4:5], v21 offset0:82 offset1:115
	s_waitcnt lgkmcnt(0)
	v_cvt_pk_bf16_f32 v3, v4, v5
	ds_read2_b32 v[4:5], v21 offset0:148 offset1:181
	s_waitcnt lgkmcnt(0)
	v_cvt_pk_bf16_f32 v4, v4, v5
	ds_read2_b32 v[6:7], v21 offset0:214 offset1:247
	s_waitcnt lgkmcnt(0)
	v_cvt_pk_bf16_f32 v5, v6, v7
	ds_read2_b32 v[6:7], v21 offset0:24 offset1:57
	global_store_dwordx4 v[10:11], v[2:5], off
	v_lshlrev_b32_e32 v22, 1, v34
	v_readlane_b32 s40, v252, 11
	s_waitcnt lgkmcnt(0)
	v_cvt_pk_bf16_f32 v2, v6, v7
	ds_read2_b32 v[4:5], v21 offset0:90 offset1:123
	s_waitcnt lgkmcnt(0)
	v_cvt_pk_bf16_f32 v3, v4, v5
	ds_read2_b32 v[4:5], v21 offset0:156 offset1:189
	s_waitcnt lgkmcnt(0)
	v_cvt_pk_bf16_f32 v4, v4, v5
	ds_read2_b32 v[6:7], v21 offset0:222 offset1:255
	s_waitcnt lgkmcnt(0)
	v_cvt_pk_bf16_f32 v5, v6, v7
	v_lshl_add_u64 v[6:7], v[8:9], 0, v[22:23]
	global_store_dwordx4 v[6:7], v[2:5], off
	s_waitcnt lgkmcnt(0)
	v_readlane_b32 s41, v252, 12
	v_readlane_b32 s42, v252, 13
	v_readlane_b32 s43, v252, 14
	v_readlane_b32 s44, v252, 15
	v_readlane_b32 s45, v252, 16
	v_readlane_b32 s46, v252, 17
	v_readlane_b32 s47, v252, 18

; #define LAS __attribute__((address_space(3)))
; __device__ __forceinline__ void transpose_item(const float* W, size_t ldw, bf16* WT, size_t K, LAS float* scr, int lane) {
; #pragma unroll 8
;     for (int i = 0; i < 32; ++i) { const int kk = 2 * i + (lane >> 5); scr[kk * 33 + (lane & 31)] = W[(size_t)kk * ldw + (lane & 31)]; }
.LBB0_33:
	s_lshl_b32 s23, s9, 1
	s_lshl_b32 s25, s10, 1
	v_or_b32_e32 v22, s25, v18
	s_add_i32 s28, s23, 4
	s_add_i32 s29, s25, 4
	v_mov_b32_e32 v7, v23
	s_add_i32 s31, s25, 8
	v_lshlrev_b64 v[52:53], 13, v[22:23]
	v_mad_u64_u32 v[54:55], s[26:27], v22, s14, v[24:25]
	v_or_b32_e32 v6, s28, v1
	v_or_b32_e32 v22, s29, v18
	v_mov_b32_e32 v5, v23
	v_or_b32_e32 v4, s23, v1
	s_add_i32 s34, s25, 12
	v_lshlrev_b64 v[56:57], 13, v[6:7]
	v_lshlrev_b64 v[58:59], 13, v[22:23]
	v_mad_u64_u32 v[60:61], s[26:27], v22, s14, v[24:25]
	v_or_b32_e32 v22, s31, v18
	s_add_i32 s30, s23, 8
	s_add_i32 s33, s23, 12
	s_add_i32 s36, s25, 16
	v_lshlrev_b64 v[50:51], 13, v[4:5]
	v_lshl_add_u64 v[52:53], v[2:3], 0, v[52:53]
	v_lshl_add_u64 v[56:57], v[2:3], 0, v[56:57]
	v_lshlrev_b64 v[74:75], 13, v[22:23]
	v_mad_u64_u32 v[76:77], s[26:27], v22, s14, v[24:25]
	v_or_b32_e32 v22, s34, v18
	v_mov_b32_e32 v9, v23
	v_mov_b32_e32 v11, v23
	s_add_i32 s35, s23, 16
	s_add_i32 s38, s25, 20
	v_or_b32_e32 v8, s30, v1
	v_or_b32_e32 v10, s33, v1
	v_lshl_add_u64 v[50:51], v[2:3], 0, v[50:51]
	v_lshl_add_u64 v[58:59], v[2:3], 0, v[58:59]
	global_load_dword v37, v[52:53], off
	global_load_dword v39, v[50:51], off
	global_load_dword v41, v[58:59], off
	global_load_dword v43, v[56:57], off
	v_lshlrev_b64 v[52:53], 13, v[22:23]
	v_mad_u64_u32 v[56:57], s[26:27], v22, s14, v[24:25]
	v_or_b32_e32 v22, s36, v18
	v_mov_b32_e32 v13, v23
	s_add_i32 s37, s23, 20
	s_add_i32 s40, s25, 24
	v_or_b32_e32 v12, s35, v1
	v_lshlrev_b64 v[62:63], 13, v[8:9]
	v_lshlrev_b64 v[64:65], 13, v[10:11]
	v_lshl_add_u64 v[50:51], v[2:3], 0, v[74:75]
	v_lshl_add_u64 v[52:53], v[2:3], 0, v[52:53]
	v_lshlrev_b64 v[58:59], 13, v[22:23]
	v_mad_u64_u32 v[74:75], s[26:27], v22, s14, v[24:25]
	v_or_b32_e32 v22, s38, v18
	v_mov_b32_e32 v15, v23
	s_add_i32 s25, s25, 28
	v_or_b32_e32 v14, s37, v1
	v_lshlrev_b64 v[66:67], 13, v[12:13]
	v_lshl_add_u64 v[62:63], v[2:3], 0, v[62:63]
	v_lshl_add_u64 v[64:65], v[2:3], 0, v[64:65]
	global_load_dword v45, v[50:51], off
	global_load_dword v49, v[62:63], off
	global_load_dword v55, v[52:53], off
	global_load_dword v57, v[64:65], off
	v_lshl_add_u64 v[50:51], v[2:3], 0, v[58:59]
	v_lshlrev_b64 v[52:53], 13, v[22:23]
	v_mad_u64_u32 v[58:59], s[26:27], v22, s14, v[24:25]
	v_or_b32_e32 v22, s40, v18
	s_add_i32 s39, s23, 24
	s_add_i32 s23, s23, 28
	v_lshlrev_b64 v[68:69], 13, v[14:15]
	v_lshl_add_u64 v[66:67], v[2:3], 0, v[66:67]
	v_lshl_add_u64 v[52:53], v[2:3], 0, v[52:53]
	v_lshlrev_b64 v[62:63], 13, v[22:23]
	v_mad_u64_u32 v[64:65], s[26:27], v22, s14, v[24:25]
	v_or_b32_e32 v22, s25, v18
	v_mov_b32_e32 v17, v23
	v_mov_b32_e32 v47, v23
	v_or_b32_e32 v16, s39, v1
	v_or_b32_e32 v46, s23, v1
	v_lshl_add_u64 v[68:69], v[2:3], 0, v[68:69]
	global_load_dword v59, v[50:51], off
	global_load_dword v61, v[66:67], off
	global_load_dword v65, v[52:53], off
	s_nop 0
	global_load_dword v66, v[68:69], off
	v_lshlrev_b64 v[52:53], 13, v[22:23]
	v_lshlrev_b64 v[70:71], 13, v[16:17]
	v_lshlrev_b64 v[72:73], 13, v[46:47]
	v_lshl_add_u64 v[50:51], v[2:3], 0, v[62:63]
	v_lshl_add_u64 v[52:53], v[2:3], 0, v[52:53]
	v_lshl_add_u64 v[70:71], v[2:3], 0, v[70:71]
	v_lshl_add_u64 v[72:73], v[2:3], 0, v[72:73]
	global_load_dword v62, v[50:51], off
	global_load_dword v63, v[70:71], off
	s_nop 0
	global_load_dword v52, v[52:53], off
	s_nop 0
	global_load_dword v53, v[72:73], off
	s_add_i32 s10, s10, 16
	s_add_i32 s9, s9, 16
	s_add_i32 s11, s11, -16
	s_cmp_lg_u32 s11, 0
	v_mad_u64_u32 v[4:5], s[26:27], v4, s14, v[24:25]
	v_mad_u64_u32 v[6:7], s[26:27], v6, s14, v[24:25]
	v_mad_u64_u32 v[8:9], s[26:27], v8, s14, v[24:25]
	v_mad_u64_u32 v[10:11], s[26:27], v10, s14, v[24:25]
	v_mad_u64_u32 v[12:13], s[26:27], v12, s14, v[24:25]
	v_mad_u64_u32 v[14:15], s[26:27], v14, s14, v[24:25]
	v_mad_u64_u32 v[16:17], s[26:27], v16, s14, v[24:25]
	v_mad_u64_u32 v[46:47], s[26:27], v46, s14, v[24:25]
	v_mad_u64_u32 v[50:51], s[26:27], v22, s14, v[24:25]
	v_mov_b32_e32 v119, v23
	s_lshl_b32 s23, s9, 1
	s_lshl_b32 s25, s10, 1
	v_or_b32_e32 v118, s25, v18
	s_add_i32 s28, s23, 4
	s_add_i32 s29, s25, 4
	v_mov_b32_e32 v103, v119
	s_add_i32 s31, s25, 8
	v_lshlrev_b64 v[148:149], 13, v[118:119]
	v_mad_u64_u32 v[150:151], s[26:27], v118, s14, v[24:25]
	v_or_b32_e32 v102, s28, v1
	v_or_b32_e32 v118, s29, v18
	v_mov_b32_e32 v101, v119
	v_or_b32_e32 v100, s23, v1
	s_add_i32 s34, s25, 12
	v_lshlrev_b64 v[152:153], 13, v[102:103]
	v_lshlrev_b64 v[154:155], 13, v[118:119]
	v_mad_u64_u32 v[156:157], s[26:27], v118, s14, v[24:25]
	v_or_b32_e32 v118, s31, v18
	s_add_i32 s30, s23, 8
	s_add_i32 s33, s23, 12
	s_add_i32 s36, s25, 16
	v_lshlrev_b64 v[146:147], 13, v[100:101]
	v_lshl_add_u64 v[148:149], v[2:3], 0, v[148:149]
	v_lshl_add_u64 v[152:153], v[2:3], 0, v[152:153]
	v_lshlrev_b64 v[170:171], 13, v[118:119]
	v_mad_u64_u32 v[172:173], s[26:27], v118, s14, v[24:25]
	v_or_b32_e32 v118, s34, v18
	v_mov_b32_e32 v105, v119
	v_mov_b32_e32 v107, v119
	s_add_i32 s35, s23, 16
	s_add_i32 s38, s25, 20
	v_or_b32_e32 v104, s30, v1
	v_or_b32_e32 v106, s33, v1
	v_lshl_add_u64 v[146:147], v[2:3], 0, v[146:147]
	v_lshl_add_u64 v[154:155], v[2:3], 0, v[154:155]
	global_load_dword v133, v[148:149], off
	global_load_dword v135, v[146:147], off
	global_load_dword v137, v[154:155], off
	global_load_dword v139, v[152:153], off
	v_lshlrev_b64 v[148:149], 13, v[118:119]
	v_mad_u64_u32 v[152:153], s[26:27], v118, s14, v[24:25]
	v_or_b32_e32 v118, s36, v18
	v_mov_b32_e32 v109, v119
	s_add_i32 s37, s23, 20
	s_add_i32 s40, s25, 24
	v_or_b32_e32 v108, s35, v1
	v_lshlrev_b64 v[158:159], 13, v[104:105]
	v_lshlrev_b64 v[160:161], 13, v[106:107]
	v_lshl_add_u64 v[146:147], v[2:3], 0, v[170:171]
; #define LAS __attribute__((address_space(3)))
; __device__ __forceinline__ unsigned cvt_pk_bf16(float lo, float hi) { unsigned r; asm volatile("v_cvt_pk_bf16_f32 %0, %1, %2" : "=v"(r) : "v"(lo), "v"(hi)); return r; }
; __device__ __forceinline__ void transpose_item(const float* W, size_t ldw, bf16* WT, size_t K, LAS float* scr, int lane) {
;     ...
;     for (int i = 0; i < 32; ++i) { const int kk = 2 * i + (lane >> 5); scr[kk * 33 + (lane & 31)] = W[(size_t)kk * ldw + (lane & 31)]; }
;     asm volatile("s_waitcnt lgkmcnt(0)" ::: "memory");
;     const int c = lane & 7;
; #pragma unroll
;     for (int j = 0; j < 4; ++j) { const int n = (lane >> 3) + 8 * j; const LAS float* s = scr + (8 * c) * 33 + n;
;         u32x4 o; o.x = cvt_pk_bf16(s[0 * 33], s[1 * 33]); o.y = cvt_pk_bf16(s[2 * 33], s[3 * 33]); o.z = cvt_pk_bf16(s[4 * 33], s[5 * 33]); o.w = cvt_pk_bf16(s[6 * 33], s[7 * 33]);
;         *(u32x4*)(WT + (size_t)n * K + 8 * c) = o; }
; __device__ __forceinline__ void phase_prologue(const In& in, unsigned char* ws, LAS unsigned char* lds, int tid, int wave, int lane) {
;     ...
;         if (r < 3 * I_B) {
;             const int n = r / I_B, q = r % I_B, nblk = D / 32, kb = q / nblk, nb = q % nblk, n0 = nb * 32, k0 = kb * 64;
;             const float* W = in.w_branch + ((size_t)(l * 3 + n) * MIXW + k0) * D + n0;
;             bf16* WT = (bf16*)(ws + WS_WB + (size_t)l * SZ_WB) + ((size_t)n * D + n0) * MIXW + k0;
;             transpose_item(W, D, WT, MIXW, scr, lane);
	v_lshl_add_u64 v[148:149], v[2:3], 0, v[148:149]
	v_lshlrev_b64 v[154:155], 13, v[118:119]
	v_mad_u64_u32 v[170:171], s[26:27], v118, s14, v[24:25]
	v_or_b32_e32 v118, s38, v18
	v_mov_b32_e32 v111, v119
	s_add_i32 s25, s25, 28
	v_or_b32_e32 v110, s37, v1
	v_lshlrev_b64 v[162:163], 13, v[108:109]
	v_lshl_add_u64 v[158:159], v[2:3], 0, v[158:159]
	v_lshl_add_u64 v[160:161], v[2:3], 0, v[160:161]
	global_load_dword v141, v[146:147], off
	global_load_dword v145, v[158:159], off
	global_load_dword v151, v[148:149], off
	global_load_dword v153, v[160:161], off
	v_lshl_add_u64 v[146:147], v[2:3], 0, v[154:155]
	v_lshlrev_b64 v[148:149], 13, v[118:119]
	v_mad_u64_u32 v[154:155], s[26:27], v118, s14, v[24:25]
	v_or_b32_e32 v118, s40, v18
	s_add_i32 s39, s23, 24
	s_add_i32 s23, s23, 28
	v_lshlrev_b64 v[164:165], 13, v[110:111]
	v_lshl_add_u64 v[162:163], v[2:3], 0, v[162:163]
	v_lshl_add_u64 v[148:149], v[2:3], 0, v[148:149]
	v_lshlrev_b64 v[158:159], 13, v[118:119]
	v_mad_u64_u32 v[160:161], s[26:27], v118, s14, v[24:25]
	v_or_b32_e32 v118, s25, v18
	v_mov_b32_e32 v113, v119
	v_mov_b32_e32 v143, v119
	v_or_b32_e32 v112, s39, v1
	v_or_b32_e32 v142, s23, v1
	v_lshl_add_u64 v[164:165], v[2:3], 0, v[164:165]
	global_load_dword v155, v[146:147], off
	global_load_dword v157, v[162:163], off
	global_load_dword v161, v[148:149], off
	s_nop 0
	global_load_dword v162, v[164:165], off
	v_lshlrev_b64 v[148:149], 13, v[118:119]
	v_lshlrev_b64 v[166:167], 13, v[112:113]
	v_lshlrev_b64 v[168:169], 13, v[142:143]
	v_lshl_add_u64 v[146:147], v[2:3], 0, v[158:159]
	v_lshl_add_u64 v[148:149], v[2:3], 0, v[148:149]
	v_lshl_add_u64 v[166:167], v[2:3], 0, v[166:167]
	v_lshl_add_u64 v[168:169], v[2:3], 0, v[168:169]
	global_load_dword v158, v[146:147], off
	global_load_dword v159, v[166:167], off
	s_nop 0
	global_load_dword v148, v[148:149], off
	s_nop 0
	global_load_dword v149, v[168:169], off
	s_add_i32 s10, s10, 16
	s_add_i32 s9, s9, 16
	s_add_i32 s11, s11, -16
	s_cmp_lg_u32 s11, 0
	v_mad_u64_u32 v[100:101], s[26:27], v100, s14, v[24:25]
	v_mad_u64_u32 v[102:103], s[26:27], v102, s14, v[24:25]
	v_mad_u64_u32 v[104:105], s[26:27], v104, s14, v[24:25]
	v_mad_u64_u32 v[106:107], s[26:27], v106, s14, v[24:25]
	v_mad_u64_u32 v[108:109], s[26:27], v108, s14, v[24:25]
	v_mad_u64_u32 v[110:111], s[26:27], v110, s14, v[24:25]
	v_mad_u64_u32 v[112:113], s[26:27], v112, s14, v[24:25]
	v_mad_u64_u32 v[142:143], s[26:27], v142, s14, v[24:25]
	v_mad_u64_u32 v[146:147], s[26:27], v118, s14, v[24:25]
	s_waitcnt vmcnt(31)
	ds_write_b32 v54, v37
	s_waitcnt vmcnt(30)
	ds_write_b32 v4, v39
	s_waitcnt vmcnt(29)
	ds_write_b32 v60, v41
	s_waitcnt vmcnt(28)
	ds_write_b32 v6, v43
	s_waitcnt vmcnt(27)
	ds_write_b32 v76, v45
	s_waitcnt vmcnt(26)
	ds_write_b32 v8, v49
	s_waitcnt vmcnt(25)
	ds_write_b32 v56, v55
	s_waitcnt vmcnt(24)
	ds_write_b32 v10, v57
	s_waitcnt vmcnt(23)
	ds_write_b32 v74, v59
	s_waitcnt vmcnt(22)
	ds_write_b32 v12, v61
	s_waitcnt vmcnt(21)
	ds_write_b32 v58, v65
	s_waitcnt vmcnt(20)
	ds_write_b32 v14, v66
	s_waitcnt vmcnt(19)
	ds_write_b32 v64, v62
	s_waitcnt vmcnt(18)
	ds_write_b32 v16, v63
	s_waitcnt vmcnt(17)
	ds_write_b32 v50, v52
	s_waitcnt vmcnt(16)
	ds_write_b32 v46, v53
	s_waitcnt vmcnt(15)
	ds_write_b32 v150, v133
	s_waitcnt vmcnt(14)
	ds_write_b32 v100, v135
	s_waitcnt vmcnt(13)
	ds_write_b32 v156, v137
	s_waitcnt vmcnt(12)
	ds_write_b32 v102, v139
	s_waitcnt vmcnt(11)
	ds_write_b32 v172, v141
	s_waitcnt vmcnt(10)
	ds_write_b32 v104, v145
	s_waitcnt vmcnt(9)
	ds_write_b32 v152, v151
	s_waitcnt vmcnt(8)
	ds_write_b32 v106, v153
	s_waitcnt vmcnt(7)
	ds_write_b32 v170, v155
	s_waitcnt vmcnt(6)
	ds_write_b32 v108, v157
	s_waitcnt vmcnt(5)
	ds_write_b32 v154, v161
	s_waitcnt vmcnt(4)
	ds_write_b32 v110, v162
	s_waitcnt vmcnt(3)
	ds_write_b32 v160, v158
	s_waitcnt vmcnt(2)
	ds_write_b32 v112, v159
	s_waitcnt vmcnt(1)
	ds_write_b32 v146, v148
	s_waitcnt vmcnt(0)
	ds_write_b32 v142, v149
	s_mul_i32 s23, s6, 0xc00000
	s_lshl_b64 s[10:11], s[0:1], 22
	s_lshl_b32 s0, s8, 11
	v_readlane_b32 s2, v252, 55
	s_mul_hi_i32 s9, s6, 0xc00000
	s_add_u32 s8, s2, s23
	v_readlane_b32 s2, v252, 56
	s_addc_u32 s9, s2, s9
	s_add_u32 s8, s8, s10
	s_addc_u32 s9, s9, s11
	s_add_u32 s0, s8, s0
	s_waitcnt lgkmcnt(0)
	s_addc_u32 s9, s9, 0
	s_lshl_b32 s7, s7, 1
	ds_read2_b32 v[2:3], v21 offset1:33
	s_add_u32 s8, s0, s7
	s_waitcnt lgkmcnt(0)
	v_cvt_pk_bf16_f32 v2, v2, v3
	ds_read2_b32 v[4:5], v21 offset0:66 offset1:99
	s_addc_u32 s9, s9, 0
	v_lshlrev_b32_e32 v22, 1, v26
	s_waitcnt lgkmcnt(0)
	v_cvt_pk_bf16_f32 v3, v4, v5
	ds_read2_b32 v[4:5], v21 offset0:132 offset1:165
	v_lshl_add_u64 v[8:9], s[8:9], 0, v[22:23]
	v_mov_b32_e32 v37, v23
	s_waitcnt lgkmcnt(0)
	v_cvt_pk_bf16_f32 v4, v4, v5
	ds_read2_b32 v[6:7], v21 offset0:198 offset1:231
	s_waitcnt lgkmcnt(0)
	v_cvt_pk_bf16_f32 v5, v6, v7
	v_lshl_add_u64 v[10:11], v[8:9], 0, v[36:37]
	ds_read2_b32 v[6:7], v21 offset0:8 offset1:41
	global_store_dwordx4 v[10:11], v[2:5], off
	v_mov_b32_e32 v39, v23
	v_lshl_add_u64 v[10:11], v[8:9], 0, v[38:39]
	s_waitcnt lgkmcnt(0)
	v_cvt_pk_bf16_f32 v2, v6, v7
	ds_read2_b32 v[4:5], v21 offset0:74 offset1:107
	s_waitcnt lgkmcnt(0)
	v_cvt_pk_bf16_f32 v3, v4, v5
	ds_read2_b32 v[4:5], v21 offset0:140 offset1:173
	s_waitcnt lgkmcnt(0)
	v_cvt_pk_bf16_f32 v4, v4, v5
	ds_read2_b32 v[6:7], v21 offset0:206 offset1:239
	s_waitcnt lgkmcnt(0)
	v_cvt_pk_bf16_f32 v5, v6, v7
	ds_read2_b32 v[6:7], v21 offset0:16 offset1:49
	global_store_dwordx4 v[10:11], v[2:5], off
	v_mov_b32_e32 v41, v23
	v_lshl_add_u64 v[10:11], v[8:9], 0, v[40:41]
	s_waitcnt lgkmcnt(0)
	v_cvt_pk_bf16_f32 v2, v6, v7
	ds_read2_b32 v[4:5], v21 offset0:82 offset1:115
	s_waitcnt lgkmcnt(0)
	v_cvt_pk_bf16_f32 v3, v4, v5
	ds_read2_b32 v[4:5], v21 offset0:148 offset1:181
	s_waitcnt lgkmcnt(0)
	v_cvt_pk_bf16_f32 v4, v4, v5
	ds_read2_b32 v[6:7], v21 offset0:214 offset1:247
	s_waitcnt lgkmcnt(0)
	v_cvt_pk_bf16_f32 v5, v6, v7
	ds_read2_b32 v[6:7], v21 offset0:24 offset1:57
	global_store_dwordx4 v[10:11], v[2:5], off
	v_mov_b32_e32 v43, v23
	v_readlane_b32 s40, v252, 11
	s_waitcnt lgkmcnt(0)
	v_cvt_pk_bf16_f32 v2, v6, v7
	ds_read2_b32 v[4:5], v21 offset0:90 offset1:123
	s_waitcnt lgkmcnt(0)
	v_cvt_pk_bf16_f32 v3, v4, v5
	ds_read2_b32 v[4:5], v21 offset0:156 offset1:189
	s_waitcnt lgkmcnt(0)
	v_cvt_pk_bf16_f32 v4, v4, v5
	ds_read2_b32 v[6:7], v21 offset0:222 offset1:255
	s_waitcnt lgkmcnt(0)
	v_cvt_pk_bf16_f32 v5, v6, v7
	v_lshl_add_u64 v[6:7], v[8:9], 0, v[42:43]
	global_store_dwordx4 v[6:7], v[2:5], off
	s_waitcnt lgkmcnt(0)
	v_readlane_b32 s41, v252, 12
	v_readlane_b32 s42, v252, 13
	v_readlane_b32 s43, v252, 14
	v_readlane_b32 s44, v252, 15
	v_readlane_b32 s45, v252, 16
	v_readlane_b32 s46, v252, 17
	v_readlane_b32 s47, v252, 18

; #define LAS __attribute__((address_space(3)))
; __device__ __forceinline__ void transpose_item(const float* W, size_t ldw, bf16* WT, size_t K, LAS float* scr, int lane) {
; #pragma unroll 8
;     for (int i = 0; i < 32; ++i) { const int kk = 2 * i + (lane >> 5); scr[kk * 33 + (lane & 31)] = W[(size_t)kk * ldw + (lane & 31)]; }
.LBB0_38:
	s_lshl_b32 s26, s11, 1
	s_lshl_b32 s27, s23, 1
	v_or_b32_e32 v37, s27, v18
	s_add_i32 s28, s26, 4
	s_add_i32 s29, s27, 4
	s_add_i32 s30, s26, 8
	s_add_i32 s31, s27, 8
	s_add_i32 s33, s26, 12
	s_add_i32 s34, s27, 12
	s_add_i32 s35, s26, 16
	s_add_i32 s36, s27, 16
	s_add_i32 s37, s26, 20
	s_add_i32 s38, s27, 20
	s_add_i32 s39, s26, 24
	s_add_i32 s40, s27, 24
	s_add_i32 s41, s26, 28
	s_add_i32 s42, s27, 28
	v_or_b32_e32 v22, s26, v1
	v_mad_u64_u32 v[4:5], s[26:27], v37, s17, v[2:3]
	v_or_b32_e32 v39, s28, v1
	v_or_b32_e32 v41, s29, v18
	v_or_b32_e32 v43, s30, v1
	v_or_b32_e32 v45, s31, v18
	v_or_b32_e32 v49, s33, v1
	v_or_b32_e32 v66, s34, v18
	v_or_b32_e32 v67, s35, v1
	v_or_b32_e32 v68, s36, v18
	v_or_b32_e32 v69, s37, v1
	v_or_b32_e32 v70, s38, v18
	v_or_b32_e32 v71, s39, v1
	v_or_b32_e32 v72, s40, v18
	v_or_b32_e32 v73, s41, v1
	v_or_b32_e32 v74, s42, v18
	v_mad_u64_u32 v[6:7], s[26:27], v22, s17, v[2:3]
	v_mad_u64_u32 v[8:9], s[26:27], v41, s17, v[2:3]
	v_mad_u64_u32 v[10:11], s[26:27], v39, s17, v[2:3]
	v_mad_u64_u32 v[12:13], s[26:27], v45, s17, v[2:3]
	v_mad_u64_u32 v[14:15], s[26:27], v43, s17, v[2:3]
	v_mad_u64_u32 v[16:17], s[26:27], v66, s17, v[2:3]
	v_mad_u64_u32 v[46:47], s[26:27], v49, s17, v[2:3]
	v_mad_u64_u32 v[50:51], s[26:27], v68, s17, v[2:3]
	v_mad_u64_u32 v[52:53], s[26:27], v67, s17, v[2:3]
	v_mad_u64_u32 v[54:55], s[26:27], v70, s17, v[2:3]
	v_mad_u64_u32 v[56:57], s[26:27], v69, s17, v[2:3]
	v_mad_u64_u32 v[58:59], s[26:27], v72, s17, v[2:3]
	v_mad_u64_u32 v[60:61], s[26:27], v71, s17, v[2:3]
	v_mad_u64_u32 v[62:63], s[26:27], v74, s17, v[2:3]
	v_mad_u64_u32 v[64:65], s[26:27], v73, s17, v[2:3]
	global_load_dword v75, v[4:5], off
	global_load_dword v76, v[6:7], off
	global_load_dword v77, v[8:9], off
	global_load_dword v78, v[10:11], off
	global_load_dword v79, v[12:13], off
	global_load_dword v80, v[14:15], off
	global_load_dword v81, v[16:17], off
	global_load_dword v82, v[46:47], off
	global_load_dword v83, v[50:51], off
	global_load_dword v84, v[52:53], off
	global_load_dword v85, v[54:55], off
	global_load_dword v86, v[56:57], off
	global_load_dword v87, v[58:59], off
	global_load_dword v88, v[60:61], off
	global_load_dword v89, v[62:63], off
	global_load_dword v90, v[64:65], off
	s_add_i32 s23, s23, 16
	s_add_i32 s11, s11, 16
	s_add_i32 s25, s25, -16
	v_mad_u64_u32 v[4:5], s[26:27], v37, s14, v[24:25]
	s_cmp_lg_u32 s25, 0
	v_mad_u64_u32 v[6:7], s[26:27], v22, s14, v[24:25]
	v_mad_u64_u32 v[8:9], s[26:27], v41, s14, v[24:25]
	v_mad_u64_u32 v[10:11], s[26:27], v39, s14, v[24:25]
	v_mad_u64_u32 v[12:13], s[26:27], v45, s14, v[24:25]
	v_mad_u64_u32 v[14:15], s[26:27], v43, s14, v[24:25]
	v_mad_u64_u32 v[16:17], s[26:27], v66, s14, v[24:25]
	v_mad_u64_u32 v[46:47], s[26:27], v49, s14, v[24:25]
	v_mad_u64_u32 v[50:51], s[26:27], v68, s14, v[24:25]
	v_mad_u64_u32 v[52:53], s[26:27], v67, s14, v[24:25]
	v_mad_u64_u32 v[54:55], s[26:27], v70, s14, v[24:25]
	v_mad_u64_u32 v[56:57], s[26:27], v69, s14, v[24:25]
	v_mad_u64_u32 v[58:59], s[26:27], v72, s14, v[24:25]
	v_mad_u64_u32 v[60:61], s[26:27], v71, s14, v[24:25]
	v_mad_u64_u32 v[62:63], s[26:27], v74, s14, v[24:25]
	v_mad_u64_u32 v[64:65], s[26:27], v73, s14, v[24:25]
	s_lshl_b32 s26, s11, 1
	s_lshl_b32 s27, s23, 1
	v_or_b32_e32 v133, s27, v18
	s_add_i32 s28, s26, 4
	s_add_i32 s29, s27, 4
	s_add_i32 s30, s26, 8
	s_add_i32 s31, s27, 8
	s_add_i32 s33, s26, 12
	s_add_i32 s34, s27, 12
	s_add_i32 s35, s26, 16
	s_add_i32 s36, s27, 16
	s_add_i32 s37, s26, 20
	s_add_i32 s38, s27, 20
	s_add_i32 s39, s26, 24
	s_add_i32 s40, s27, 24
	s_add_i32 s41, s26, 28
	s_add_i32 s42, s27, 28
	v_or_b32_e32 v118, s26, v1
	v_mad_u64_u32 v[100:101], s[26:27], v133, s17, v[2:3]
	v_or_b32_e32 v135, s28, v1
	v_or_b32_e32 v137, s29, v18
	v_or_b32_e32 v139, s30, v1
	v_or_b32_e32 v141, s31, v18
	v_or_b32_e32 v145, s33, v1
	v_or_b32_e32 v162, s34, v18
	v_or_b32_e32 v163, s35, v1
	v_or_b32_e32 v164, s36, v18
	v_or_b32_e32 v165, s37, v1
	v_or_b32_e32 v166, s38, v18
	v_or_b32_e32 v167, s39, v1
	v_or_b32_e32 v168, s40, v18
	v_or_b32_e32 v169, s41, v1
	v_or_b32_e32 v170, s42, v18
	v_mad_u64_u32 v[102:103], s[26:27], v118, s17, v[2:3]
	v_mad_u64_u32 v[104:105], s[26:27], v137, s17, v[2:3]
	v_mad_u64_u32 v[106:107], s[26:27], v135, s17, v[2:3]
	v_mad_u64_u32 v[108:109], s[26:27], v141, s17, v[2:3]
	v_mad_u64_u32 v[110:111], s[26:27], v139, s17, v[2:3]
	v_mad_u64_u32 v[112:113], s[26:27], v162, s17, v[2:3]
	v_mad_u64_u32 v[142:143], s[26:27], v145, s17, v[2:3]
	v_mad_u64_u32 v[146:147], s[26:27], v164, s17, v[2:3]
	v_mad_u64_u32 v[148:149], s[26:27], v163, s17, v[2:3]
	v_mad_u64_u32 v[150:151], s[26:27], v166, s17, v[2:3]
	v_mad_u64_u32 v[152:153], s[26:27], v165, s17, v[2:3]
	v_mad_u64_u32 v[154:155], s[26:27], v168, s17, v[2:3]
	v_mad_u64_u32 v[156:157], s[26:27], v167, s17, v[2:3]
	v_mad_u64_u32 v[158:159], s[26:27], v170, s17, v[2:3]
	v_mad_u64_u32 v[160:161], s[26:27], v169, s17, v[2:3]
	global_load_dword v171, v[100:101], off
	global_load_dword v172, v[102:103], off
	global_load_dword v173, v[104:105], off
	global_load_dword v174, v[106:107], off
	global_load_dword v175, v[108:109], off
	global_load_dword v176, v[110:111], off
	global_load_dword v177, v[112:113], off
	global_load_dword v178, v[142:143], off
	global_load_dword v179, v[146:147], off
	global_load_dword v180, v[148:149], off
	global_load_dword v181, v[150:151], off
	global_load_dword v182, v[152:153], off
	global_load_dword v183, v[154:155], off
	global_load_dword v184, v[156:157], off
	global_load_dword v185, v[158:159], off
	global_load_dword v186, v[160:161], off
	s_add_i32 s23, s23, 16
	s_add_i32 s11, s11, 16
	s_add_i32 s25, s25, -16
	v_mad_u64_u32 v[100:101], s[26:27], v133, s14, v[24:25]
	s_cmp_lg_u32 s25, 0
	v_mad_u64_u32 v[102:103], s[26:27], v118, s14, v[24:25]
	v_mad_u64_u32 v[104:105], s[26:27], v137, s14, v[24:25]
	v_mad_u64_u32 v[106:107], s[26:27], v135, s14, v[24:25]
	v_mad_u64_u32 v[108:109], s[26:27], v141, s14, v[24:25]
	v_mad_u64_u32 v[110:111], s[26:27], v139, s14, v[24:25]
	v_mad_u64_u32 v[112:113], s[26:27], v162, s14, v[24:25]
	v_mad_u64_u32 v[142:143], s[26:27], v145, s14, v[24:25]
	v_mad_u64_u32 v[146:147], s[26:27], v164, s14, v[24:25]
	v_mad_u64_u32 v[148:149], s[26:27], v163, s14, v[24:25]
	v_mad_u64_u32 v[150:151], s[26:27], v166, s14, v[24:25]
	v_mad_u64_u32 v[152:153], s[26:27], v165, s14, v[24:25]
	v_mad_u64_u32 v[154:155], s[26:27], v168, s14, v[24:25]
	v_mad_u64_u32 v[156:157], s[26:27], v167, s14, v[24:25]
	v_mad_u64_u32 v[158:159], s[26:27], v170, s14, v[24:25]
	v_mad_u64_u32 v[160:161], s[26:27], v169, s14, v[24:25]
	s_waitcnt vmcnt(31)
; #define LAS __attribute__((address_space(3)))
; __device__ __forceinline__ unsigned cvt_pk_bf16(float lo, float hi) { unsigned r; asm volatile("v_cvt_pk_bf16_f32 %0, %1, %2" : "=v"(r) : "v"(lo), "v"(hi)); return r; }
; __device__ __forceinline__ void transpose_item(const float* W, size_t ldw, bf16* WT, size_t K, LAS float* scr, int lane) {
;     ...
;     for (int i = 0; i < 32; ++i) { const int kk = 2 * i + (lane >> 5); scr[kk * 33 + (lane & 31)] = W[(size_t)kk * ldw + (lane & 31)]; }
;     asm volatile("s_waitcnt lgkmcnt(0)" ::: "memory");
;     const int c = lane & 7;
; #pragma unroll
;     for (int j = 0; j < 4; ++j) { const int n = (lane >> 3) + 8 * j; const LAS float* s = scr + (8 * c) * 33 + n;
;         u32x4 o; o.x = cvt_pk_bf16(s[0 * 33], s[1 * 33]); o.y = cvt_pk_bf16(s[2 * 33], s[3 * 33]); o.z = cvt_pk_bf16(s[4 * 33], s[5 * 33]); o.w = cvt_pk_bf16(s[6 * 33], s[7 * 33]);
;         *(u32x4*)(WT + (size_t)n * K + 8 * c) = o; }
; __device__ __forceinline__ void phase_prologue(const In& in, unsigned char* ws, LAS unsigned char* lds, int tid, int wave, int lane) {
;     ...
;         if (r < I_IN) {
;             const int kb = r / 512, nb = r % 512, k0 = kb * 64;
;             const int srcc = nb < 320 ? nb * 32 : 10256 + (nb - 320) * 32;
;             int dstr = nb < 320 ? nb * 32 : 10752 + (nb - 320) * 32;
;             if (nb < 64) { const int r0 = (nb * 32) & 255; dstr = (nb * 32 & ~255) + 128 * ((r0 & 63) >> 5) + 32 * (r0 >> 6); }
;             const float* W = in.w_in + ((size_t)l * D + k0) * NIN + srcc;
;             bf16* WT = (bf16*)(ws + WS_WIN + (size_t)l * SZ_WIN) + (size_t)dstr * D + k0;
;             transpose_item(W, NIN, WT, D, scr, lane);
	ds_write_b32 v4, v75
	s_waitcnt vmcnt(30)
	ds_write_b32 v6, v76
	s_waitcnt vmcnt(29)
	ds_write_b32 v8, v77
	s_waitcnt vmcnt(28)
	ds_write_b32 v10, v78
	s_waitcnt vmcnt(27)
	ds_write_b32 v12, v79
	s_waitcnt vmcnt(26)
	ds_write_b32 v14, v80
	s_waitcnt vmcnt(25)
	ds_write_b32 v16, v81
	s_waitcnt vmcnt(24)
	ds_write_b32 v46, v82
	s_waitcnt vmcnt(23)
	ds_write_b32 v50, v83
	s_waitcnt vmcnt(22)
	ds_write_b32 v52, v84
	s_waitcnt vmcnt(21)
	ds_write_b32 v54, v85
	s_waitcnt vmcnt(20)
	ds_write_b32 v56, v86
	s_waitcnt vmcnt(19)
	ds_write_b32 v58, v87
	s_waitcnt vmcnt(18)
	ds_write_b32 v60, v88
	s_waitcnt vmcnt(17)
	ds_write_b32 v62, v89
	s_waitcnt vmcnt(16)
	ds_write_b32 v64, v90
	s_waitcnt vmcnt(15)
	ds_write_b32 v100, v171
	s_waitcnt vmcnt(14)
	ds_write_b32 v102, v172
	s_waitcnt vmcnt(13)
	ds_write_b32 v104, v173
	s_waitcnt vmcnt(12)
	ds_write_b32 v106, v174
	s_waitcnt vmcnt(11)
	ds_write_b32 v108, v175
	s_waitcnt vmcnt(10)
	ds_write_b32 v110, v176
	s_waitcnt vmcnt(9)
	ds_write_b32 v112, v177
	s_waitcnt vmcnt(8)
	ds_write_b32 v142, v178
	s_waitcnt vmcnt(7)
	ds_write_b32 v146, v179
	s_waitcnt vmcnt(6)
	ds_write_b32 v148, v180
	s_waitcnt vmcnt(5)
	ds_write_b32 v150, v181
	s_waitcnt vmcnt(4)
	ds_write_b32 v152, v182
	s_waitcnt vmcnt(3)
	ds_write_b32 v154, v183
	s_waitcnt vmcnt(2)
	ds_write_b32 v156, v184
	s_waitcnt vmcnt(1)
	ds_write_b32 v158, v185
	s_waitcnt vmcnt(0)
	ds_write_b32 v160, v186
	s_add_i32 s11, s10, 0x200
	s_and_b64 s[8:9], s[8:9], exec
	s_cselect_b32 s8, s10, s11
	s_and_b32 s9, s10, 0x700
	s_lshl_b32 s10, s22, 7
	s_lshl_b32 s11, s22, 4
	s_and_b32 s10, s10, 0x80
	s_and_b32 s11, s11, 0x60
	s_or_b32 s10, s11, s10
	s_or_b32 s9, s10, s9
	s_cmp_lt_u32 s7, 64
	s_cselect_b32 s7, s9, s8
	s_mul_i32 s9, s6, 0x4200000
	s_lshl_b32 s7, s7, 12
	v_readlane_b32 s2, v252, 57
	s_mul_hi_i32 s8, s6, 0x4200000
	s_add_u32 s9, s2, s9
	v_readlane_b32 s2, v252, 58
	s_addc_u32 s8, s2, s8
	s_add_u32 s7, s9, s7
	s_waitcnt lgkmcnt(0)
	s_addc_u32 s9, s8, 0
	s_lshl_b32 s0, s0, 1
	ds_read2_b32 v[2:3], v21 offset1:33
	s_add_u32 s8, s7, s0
	s_waitcnt lgkmcnt(0)
	v_cvt_pk_bf16_f32 v2, v2, v3
	ds_read2_b32 v[4:5], v21 offset0:66 offset1:99
	s_addc_u32 s9, s9, 0
	v_lshlrev_b32_e32 v22, 1, v26
	s_waitcnt lgkmcnt(0)
	v_cvt_pk_bf16_f32 v3, v4, v5
	ds_read2_b32 v[4:5], v21 offset0:132 offset1:165
	v_lshl_add_u64 v[8:9], s[8:9], 0, v[22:23]
	v_lshlrev_b32_e32 v22, 1, v28
	s_waitcnt lgkmcnt(0)
	v_cvt_pk_bf16_f32 v4, v4, v5
	ds_read2_b32 v[6:7], v21 offset0:198 offset1:231
	s_waitcnt lgkmcnt(0)
	v_cvt_pk_bf16_f32 v5, v6, v7
	v_lshl_add_u64 v[10:11], v[8:9], 0, v[22:23]
	ds_read2_b32 v[6:7], v21 offset0:8 offset1:41
	global_store_dwordx4 v[10:11], v[2:5], off
	v_lshlrev_b32_e32 v22, 1, v30
	v_lshl_add_u64 v[10:11], v[8:9], 0, v[22:23]
	s_waitcnt lgkmcnt(0)
	v_cvt_pk_bf16_f32 v2, v6, v7
	ds_read2_b32 v[4:5], v21 offset0:74 offset1:107
	s_waitcnt lgkmcnt(0)
	v_cvt_pk_bf16_f32 v3, v4, v5
	ds_read2_b32 v[4:5], v21 offset0:140 offset1:173
	s_waitcnt lgkmcnt(0)
	v_cvt_pk_bf16_f32 v4, v4, v5
	ds_read2_b32 v[6:7], v21 offset0:206 offset1:239
	s_waitcnt lgkmcnt(0)
	v_cvt_pk_bf16_f32 v5, v6, v7
	ds_read2_b32 v[6:7], v21 offset0:16 offset1:49
	global_store_dwordx4 v[10:11], v[2:5], off
	v_lshlrev_b32_e32 v22, 1, v32
	v_lshl_add_u64 v[10:11], v[8:9], 0, v[22:23]
	s_waitcnt lgkmcnt(0)
	v_cvt_pk_bf16_f32 v2, v6, v7
	ds_read2_b32 v[4:5], v21 offset0:82 offset1:115
	s_waitcnt lgkmcnt(0)
	v_cvt_pk_bf16_f32 v3, v4, v5
	ds_read2_b32 v[4:5], v21 offset0:148 offset1:181
	s_waitcnt lgkmcnt(0)
	v_cvt_pk_bf16_f32 v4, v4, v5
	ds_read2_b32 v[6:7], v21 offset0:214 offset1:247
	s_waitcnt lgkmcnt(0)
	v_cvt_pk_bf16_f32 v5, v6, v7
	ds_read2_b32 v[6:7], v21 offset0:24 offset1:57
	global_store_dwordx4 v[10:11], v[2:5], off
	v_lshlrev_b32_e32 v22, 1, v34
	v_readlane_b32 s40, v252, 11
	s_waitcnt lgkmcnt(0)
	v_cvt_pk_bf16_f32 v2, v6, v7
	ds_read2_b32 v[4:5], v21 offset0:90 offset1:123
	s_waitcnt lgkmcnt(0)
	v_cvt_pk_bf16_f32 v3, v4, v5
	ds_read2_b32 v[4:5], v21 offset0:156 offset1:189
	s_waitcnt lgkmcnt(0)
	v_cvt_pk_bf16_f32 v4, v4, v5
	ds_read2_b32 v[6:7], v21 offset0:222 offset1:255
	s_waitcnt lgkmcnt(0)
	v_cvt_pk_bf16_f32 v5, v6, v7
	v_lshl_add_u64 v[6:7], v[8:9], 0, v[22:23]
	global_store_dwordx4 v[6:7], v[2:5], off
	s_waitcnt lgkmcnt(0)
	v_readlane_b32 s41, v252, 12
	v_readlane_b32 s42, v252, 13
	v_readlane_b32 s43, v252, 14
	v_readlane_b32 s44, v252, 15
	v_readlane_b32 s45, v252, 16
	v_readlane_b32 s46, v252, 17
	v_readlane_b32 s47, v252, 18

; #define LAS __attribute__((address_space(3)))
; __device__ __forceinline__ void transpose_item(const float* W, size_t ldw, bf16* WT, size_t K, LAS float* scr, int lane) {
; #pragma unroll 8
;     for (int i = 0; i < 32; ++i) { const int kk = 2 * i + (lane >> 5); scr[kk * 33 + (lane & 31)] = W[(size_t)kk * ldw + (lane & 31)]; }
;     asm volatile("s_waitcnt lgkmcnt(0)" ::: "memory");
.LBB0_44:
	s_lshl_b32 s29, s27, 1
	s_lshl_b32 s30, s11, 1
	v_or_b32_e32 v22, s30, v18
	s_add_i32 s33, s29, 4
	s_add_i32 s34, s30, 4
	v_mov_b32_e32 v9, v23
	s_add_i32 s35, s29, 8
	s_add_i32 s36, s30, 8
	s_add_i32 s38, s30, 12
	s_add_i32 s40, s30, 16
	s_add_i32 s42, s30, 20
	s_add_i32 s44, s30, 24
	s_add_i32 s45, s30, 28
	v_lshlrev_b64 v[54:55], 13, v[22:23]
	v_mad_u64_u32 v[56:57], s[30:31], v22, s14, v[24:25]
	v_or_b32_e32 v8, s33, v1
	v_or_b32_e32 v22, s34, v18
	v_mov_b32_e32 v7, v23
	v_mov_b32_e32 v11, v23
	v_or_b32_e32 v6, s29, v1
	s_add_i32 s37, s29, 12
	s_add_i32 s39, s29, 16
	s_add_i32 s41, s29, 20
	s_add_i32 s43, s29, 24
	s_add_i32 s29, s29, 28
	v_or_b32_e32 v10, s35, v1
	v_lshlrev_b64 v[58:59], 13, v[8:9]
	v_lshlrev_b64 v[60:61], 13, v[22:23]
	v_mad_u64_u32 v[62:63], s[30:31], v22, s14, v[24:25]
	v_or_b32_e32 v22, s36, v18
	v_mov_b32_e32 v13, v23
	v_mov_b32_e32 v15, v23
	v_mov_b32_e32 v17, v23
	v_mov_b32_e32 v47, v23
	v_mov_b32_e32 v51, v23
	v_lshlrev_b64 v[52:53], 13, v[6:7]
	v_or_b32_e32 v12, s37, v1
	v_or_b32_e32 v14, s39, v1
	v_or_b32_e32 v16, s41, v1
	v_or_b32_e32 v46, s43, v1
	v_or_b32_e32 v50, s29, v1
	v_lshl_add_u64 v[54:55], v[4:5], 0, v[54:55]
	v_lshlrev_b64 v[64:65], 13, v[10:11]
	v_lshl_add_u64 v[58:59], v[4:5], 0, v[58:59]
	v_lshlrev_b64 v[76:77], 13, v[22:23]
	v_mad_u64_u32 v[78:79], s[30:31], v22, s14, v[24:25]
	v_or_b32_e32 v22, s38, v18
	v_lshl_add_u64 v[52:53], v[4:5], 0, v[52:53]
	v_lshlrev_b64 v[66:67], 13, v[12:13]
	v_lshlrev_b64 v[68:69], 13, v[14:15]
	v_lshlrev_b64 v[70:71], 13, v[16:17]
	v_lshlrev_b64 v[72:73], 13, v[46:47]
	v_lshlrev_b64 v[74:75], 13, v[50:51]
	v_lshl_add_u64 v[60:61], v[4:5], 0, v[60:61]
	v_lshl_add_u64 v[64:65], v[4:5], 0, v[64:65]
	global_load_dword v3, v[54:55], off
	global_load_dword v37, v[52:53], off
	global_load_dword v39, v[60:61], off
	global_load_dword v41, v[58:59], off
	v_lshlrev_b64 v[54:55], 13, v[22:23]
	v_mad_u64_u32 v[58:59], s[30:31], v22, s14, v[24:25]
	v_or_b32_e32 v22, s40, v18
	v_lshl_add_u64 v[66:67], v[4:5], 0, v[66:67]
	v_lshl_add_u64 v[68:69], v[4:5], 0, v[68:69]
	v_lshl_add_u64 v[70:71], v[4:5], 0, v[70:71]
	v_lshl_add_u64 v[72:73], v[4:5], 0, v[72:73]
	v_lshl_add_u64 v[74:75], v[4:5], 0, v[74:75]
	v_lshl_add_u64 v[52:53], v[4:5], 0, v[76:77]
	global_load_dword v43, v[64:65], off
	global_load_dword v45, v[66:67], off
	global_load_dword v49, v[68:69], off
	global_load_dword v57, v[70:71], off
	global_load_dword v59, v[72:73], off
	global_load_dword v63, v[74:75], off
	v_lshl_add_u64 v[54:55], v[4:5], 0, v[54:55]
	v_lshlrev_b64 v[60:61], 13, v[22:23]
	v_mad_u64_u32 v[64:65], s[30:31], v22, s14, v[24:25]
	v_or_b32_e32 v22, s42, v18
	global_load_dword v65, v[52:53], off
	global_load_dword v70, v[54:55], off
	v_lshl_add_u64 v[52:53], v[4:5], 0, v[60:61]
	v_lshlrev_b64 v[54:55], 13, v[22:23]
	v_mad_u64_u32 v[60:61], s[30:31], v22, s14, v[24:25]
	v_or_b32_e32 v22, s44, v18
	v_mad_u64_u32 v[68:69], s[30:31], v22, s14, v[24:25]
	v_lshl_add_u64 v[54:55], v[4:5], 0, v[54:55]
	global_load_dword v61, v[52:53], off
	global_load_dword v69, v[54:55], off
	v_lshlrev_b64 v[66:67], 13, v[22:23]
	v_or_b32_e32 v22, s45, v18
	v_lshl_add_u64 v[52:53], v[4:5], 0, v[66:67]
	v_lshlrev_b64 v[54:55], 13, v[22:23]
	global_load_dword v66, v[52:53], off
	v_lshl_add_u64 v[52:53], v[4:5], 0, v[54:55]
	global_load_dword v54, v[52:53], off
	s_add_i32 s11, s11, 16
	s_add_i32 s27, s27, 16
	s_add_i32 s28, s28, -16
	s_cmp_lg_u32 s28, 0
	v_mad_u64_u32 v[6:7], s[30:31], v6, s14, v[24:25]
	v_mad_u64_u32 v[8:9], s[30:31], v8, s14, v[24:25]
	v_mad_u64_u32 v[10:11], s[30:31], v10, s14, v[24:25]
	v_mad_u64_u32 v[12:13], s[30:31], v12, s14, v[24:25]
	v_mad_u64_u32 v[14:15], s[30:31], v14, s14, v[24:25]
	v_mad_u64_u32 v[16:17], s[30:31], v16, s14, v[24:25]
	v_mad_u64_u32 v[46:47], s[30:31], v46, s14, v[24:25]
	v_mad_u64_u32 v[50:51], s[30:31], v50, s14, v[24:25]
	v_mad_u64_u32 v[52:53], s[30:31], v22, s14, v[24:25]
	v_mov_b32_e32 v121, v23
	s_lshl_b32 s29, s27, 1
	s_lshl_b32 s30, s11, 1
	v_or_b32_e32 v120, s30, v18
	s_add_i32 s33, s29, 4
	s_add_i32 s34, s30, 4
	v_mov_b32_e32 v107, v121
	s_add_i32 s35, s29, 8
	s_add_i32 s36, s30, 8
	s_add_i32 s38, s30, 12
	s_add_i32 s40, s30, 16
	s_add_i32 s42, s30, 20
	s_add_i32 s44, s30, 24
	s_add_i32 s45, s30, 28
	v_lshlrev_b64 v[152:153], 13, v[120:121]
	v_mad_u64_u32 v[154:155], s[30:31], v120, s14, v[24:25]
	v_or_b32_e32 v106, s33, v1
	v_or_b32_e32 v120, s34, v18
	v_mov_b32_e32 v105, v121
	v_mov_b32_e32 v109, v121
	v_or_b32_e32 v104, s29, v1
	s_add_i32 s37, s29, 12
	s_add_i32 s39, s29, 16
	s_add_i32 s41, s29, 20
	s_add_i32 s43, s29, 24
	s_add_i32 s29, s29, 28
	v_or_b32_e32 v108, s35, v1
	v_lshlrev_b64 v[156:157], 13, v[106:107]
	v_lshlrev_b64 v[158:159], 13, v[120:121]
	v_mad_u64_u32 v[160:161], s[30:31], v120, s14, v[24:25]
	v_or_b32_e32 v120, s36, v18
	v_mov_b32_e32 v111, v121
	v_mov_b32_e32 v113, v121
	v_mov_b32_e32 v115, v121
	v_mov_b32_e32 v145, v121
	v_mov_b32_e32 v149, v121
	v_lshlrev_b64 v[150:151], 13, v[104:105]
	v_or_b32_e32 v110, s37, v1
	v_or_b32_e32 v112, s39, v1
	v_or_b32_e32 v114, s41, v1
	v_or_b32_e32 v144, s43, v1
	v_or_b32_e32 v148, s29, v1
	v_lshl_add_u64 v[152:153], v[4:5], 0, v[152:153]
	v_lshlrev_b64 v[162:163], 13, v[108:109]
	v_lshl_add_u64 v[156:157], v[4:5], 0, v[156:157]
	v_lshlrev_b64 v[174:175], 13, v[120:121]
	v_mad_u64_u32 v[176:177], s[30:31], v120, s14, v[24:25]
	v_or_b32_e32 v120, s38, v18
	v_lshl_add_u64 v[150:151], v[4:5], 0, v[150:151]
	v_lshlrev_b64 v[164:165], 13, v[110:111]
	v_lshlrev_b64 v[166:167], 13, v[112:113]
	v_lshlrev_b64 v[168:169], 13, v[114:115]
	v_lshlrev_b64 v[170:171], 13, v[144:145]
	v_lshlrev_b64 v[172:173], 13, v[148:149]
; #define LAS __attribute__((address_space(3)))
; __device__ __forceinline__ unsigned cvt_pk_bf16(float lo, float hi) { unsigned r; asm volatile("v_cvt_pk_bf16_f32 %0, %1, %2" : "=v"(r) : "v"(lo), "v"(hi)); return r; }
; __device__ __forceinline__ void transpose_item(const float* W, size_t ldw, bf16* WT, size_t K, LAS float* scr, int lane) {
;     ...
;     for (int i = 0; i < 32; ++i) { const int kk = 2 * i + (lane >> 5); scr[kk * 33 + (lane & 31)] = W[(size_t)kk * ldw + (lane & 31)]; }
;     asm volatile("s_waitcnt lgkmcnt(0)" ::: "memory");
;     const int c = lane & 7;
; #pragma unroll
;     for (int j = 0; j < 4; ++j) { const int n = (lane >> 3) + 8 * j; const LAS float* s = scr + (8 * c) * 33 + n;
;         u32x4 o; o.x = cvt_pk_bf16(s[0 * 33], s[1 * 33]); o.y = cvt_pk_bf16(s[2 * 33], s[3 * 33]); o.z = cvt_pk_bf16(s[4 * 33], s[5 * 33]); o.w = cvt_pk_bf16(s[6 * 33], s[7 * 33]);
;         *(u32x4*)(WT + (size_t)n * K + 8 * c) = o; }
;     asm volatile("s_waitcnt lgkmcnt(0)" ::: "memory");
	v_lshl_add_u64 v[158:159], v[4:5], 0, v[158:159]
	v_lshl_add_u64 v[162:163], v[4:5], 0, v[162:163]
	global_load_dword v101, v[152:153], off
	global_load_dword v135, v[150:151], off
	global_load_dword v137, v[158:159], off
	global_load_dword v139, v[156:157], off
	v_lshlrev_b64 v[152:153], 13, v[120:121]
	v_mad_u64_u32 v[156:157], s[30:31], v120, s14, v[24:25]
	v_or_b32_e32 v120, s40, v18
	v_lshl_add_u64 v[164:165], v[4:5], 0, v[164:165]
	v_lshl_add_u64 v[166:167], v[4:5], 0, v[166:167]
	v_lshl_add_u64 v[168:169], v[4:5], 0, v[168:169]
	v_lshl_add_u64 v[170:171], v[4:5], 0, v[170:171]
	v_lshl_add_u64 v[172:173], v[4:5], 0, v[172:173]
	v_lshl_add_u64 v[150:151], v[4:5], 0, v[174:175]
	global_load_dword v141, v[162:163], off
	global_load_dword v143, v[164:165], off
	global_load_dword v147, v[166:167], off
	global_load_dword v155, v[168:169], off
	global_load_dword v157, v[170:171], off
	global_load_dword v161, v[172:173], off
	v_lshl_add_u64 v[152:153], v[4:5], 0, v[152:153]
	v_lshlrev_b64 v[158:159], 13, v[120:121]
	v_mad_u64_u32 v[162:163], s[30:31], v120, s14, v[24:25]
	v_or_b32_e32 v120, s42, v18
	global_load_dword v163, v[150:151], off
	global_load_dword v168, v[152:153], off
	v_lshl_add_u64 v[150:151], v[4:5], 0, v[158:159]
	v_lshlrev_b64 v[152:153], 13, v[120:121]
	v_mad_u64_u32 v[158:159], s[30:31], v120, s14, v[24:25]
	v_or_b32_e32 v120, s44, v18
	v_mad_u64_u32 v[166:167], s[30:31], v120, s14, v[24:25]
	v_lshl_add_u64 v[152:153], v[4:5], 0, v[152:153]
	global_load_dword v159, v[150:151], off
	global_load_dword v167, v[152:153], off
	v_lshlrev_b64 v[164:165], 13, v[120:121]
	v_or_b32_e32 v120, s45, v18
	v_lshl_add_u64 v[150:151], v[4:5], 0, v[164:165]
	v_lshlrev_b64 v[152:153], 13, v[120:121]
	global_load_dword v164, v[150:151], off
	v_lshl_add_u64 v[150:151], v[4:5], 0, v[152:153]
	global_load_dword v152, v[150:151], off
	s_add_i32 s11, s11, 16
	s_add_i32 s27, s27, 16
	s_add_i32 s28, s28, -16
	s_cmp_lg_u32 s28, 0
	v_mad_u64_u32 v[104:105], s[30:31], v104, s14, v[24:25]
	v_mad_u64_u32 v[106:107], s[30:31], v106, s14, v[24:25]
	v_mad_u64_u32 v[108:109], s[30:31], v108, s14, v[24:25]
	v_mad_u64_u32 v[110:111], s[30:31], v110, s14, v[24:25]
	v_mad_u64_u32 v[112:113], s[30:31], v112, s14, v[24:25]
	v_mad_u64_u32 v[114:115], s[30:31], v114, s14, v[24:25]
	v_mad_u64_u32 v[144:145], s[30:31], v144, s14, v[24:25]
	v_mad_u64_u32 v[148:149], s[30:31], v148, s14, v[24:25]
	v_mad_u64_u32 v[150:151], s[30:31], v120, s14, v[24:25]
	s_waitcnt vmcnt(31)
	ds_write_b32 v56, v3
	s_waitcnt vmcnt(30)
	ds_write_b32 v6, v37
	s_waitcnt vmcnt(29)
	ds_write_b32 v62, v39
	s_waitcnt vmcnt(28)
	ds_write_b32 v8, v41
	s_waitcnt vmcnt(21)
	ds_write_b32 v78, v65
	ds_write_b32 v10, v43
	s_waitcnt vmcnt(20)
	ds_write_b32 v58, v70
	ds_write_b32 v12, v45
	s_waitcnt vmcnt(19)
	ds_write_b32 v64, v61
	ds_write_b32 v14, v49
	s_waitcnt vmcnt(18)
	ds_write_b32 v60, v69
	ds_write_b32 v16, v57
	s_waitcnt vmcnt(17)
	ds_write_b32 v68, v66
	ds_write_b32 v46, v59
	s_waitcnt vmcnt(16)
	ds_write_b32 v52, v54
	ds_write_b32 v50, v63
	s_waitcnt vmcnt(15)
	ds_write_b32 v154, v101
	s_waitcnt vmcnt(14)
	ds_write_b32 v104, v135
	s_waitcnt vmcnt(13)
	ds_write_b32 v160, v137
	s_waitcnt vmcnt(12)
	ds_write_b32 v106, v139
	s_waitcnt vmcnt(5)
	ds_write_b32 v176, v163
	ds_write_b32 v108, v141
	s_waitcnt vmcnt(4)
	ds_write_b32 v156, v168
	ds_write_b32 v110, v143
	s_waitcnt vmcnt(3)
	ds_write_b32 v162, v159
	ds_write_b32 v112, v147
	s_waitcnt vmcnt(2)
	ds_write_b32 v158, v167
	ds_write_b32 v114, v155
	s_waitcnt vmcnt(1)
	ds_write_b32 v166, v164
	ds_write_b32 v144, v157
	s_waitcnt vmcnt(0)
	ds_write_b32 v150, v152
	ds_write_b32 v148, v161
	s_mul_hi_i32 s11, s26, 0x1600000
	s_mul_i32 s26, s26, 0x1600000
	v_readlane_b32 s2, v252, 59
	s_add_u32 s26, s2, s26
	v_readlane_b32 s2, v252, 60
	s_mul_hi_i32 s27, s10, 0x2c00
	s_mulk_i32 s10, 0x2c00
	s_addc_u32 s11, s2, s11
	s_add_u32 s10, s26, s10
	s_waitcnt lgkmcnt(0)
	s_addc_u32 s11, s11, s27
	s_lshl_b64 s[8:9], s[8:9], 1
	ds_read2_b32 v[4:5], v21 offset1:33
	s_add_u32 s8, s10, s8
	s_waitcnt lgkmcnt(0)
	v_cvt_pk_bf16_f32 v4, v4, v5
	ds_read2_b32 v[6:7], v21 offset0:66 offset1:99
	v_lshlrev_b32_e32 v22, 1, v26
	s_addc_u32 s9, s11, s9
	s_waitcnt lgkmcnt(0)
	v_cvt_pk_bf16_f32 v5, v6, v7
	ds_read2_b32 v[6:7], v21 offset0:132 offset1:165
	v_mov_b32_e32 v45, v23
	v_lshl_add_u64 v[10:11], s[8:9], 0, v[22:23]
	s_waitcnt lgkmcnt(0)
	v_cvt_pk_bf16_f32 v6, v6, v7
	ds_read2_b32 v[8:9], v21 offset0:198 offset1:231
	s_waitcnt lgkmcnt(0)
	v_cvt_pk_bf16_f32 v7, v8, v9
	v_lshl_add_u64 v[10:11], v[10:11], 0, v[44:45]
	ds_read2_b32 v[8:9], v21 offset0:8 offset1:41
	global_store_dwordx4 v[10:11], v[4:7], off
	v_add_co_u32_e32 v12, vcc, s19, v10
	s_waitcnt lgkmcnt(0)
	v_cvt_pk_bf16_f32 v4, v8, v9
	ds_read2_b32 v[6:7], v21 offset0:74 offset1:107
	s_waitcnt lgkmcnt(0)
	v_cvt_pk_bf16_f32 v5, v6, v7
	ds_read2_b32 v[6:7], v21 offset0:140 offset1:173
	s_waitcnt lgkmcnt(0)
	v_cvt_pk_bf16_f32 v6, v6, v7
	ds_read2_b32 v[8:9], v21 offset0:206 offset1:239
	s_waitcnt lgkmcnt(0)
	v_cvt_pk_bf16_f32 v7, v8, v9
	v_addc_co_u32_e32 v13, vcc, 0, v11, vcc
	ds_read2_b32 v[8:9], v21 offset0:16 offset1:49
	global_store_dwordx4 v[12:13], v[4:7], off
	v_add_co_u32_e32 v12, vcc, s20, v10
	s_waitcnt lgkmcnt(0)
	v_cvt_pk_bf16_f32 v4, v8, v9
	ds_read2_b32 v[6:7], v21 offset0:82 offset1:115
	s_waitcnt lgkmcnt(0)
	v_cvt_pk_bf16_f32 v5, v6, v7
	ds_read2_b32 v[6:7], v21 offset0:148 offset1:181
	s_waitcnt lgkmcnt(0)
	v_cvt_pk_bf16_f32 v6, v6, v7
	ds_read2_b32 v[8:9], v21 offset0:214 offset1:247
	s_waitcnt lgkmcnt(0)
	v_cvt_pk_bf16_f32 v7, v8, v9
	v_addc_co_u32_e32 v13, vcc, 0, v11, vcc
	ds_read2_b32 v[8:9], v21 offset0:24 offset1:57
	global_store_dwordx4 v[12:13], v[4:7], off
	v_add_co_u32_e32 v10, vcc, 0x42000, v10
	s_waitcnt lgkmcnt(0)
	v_cvt_pk_bf16_f32 v4, v8, v9
	ds_read2_b32 v[6:7], v21 offset0:90 offset1:123
	s_waitcnt lgkmcnt(0)
	v_cvt_pk_bf16_f32 v5, v6, v7
	ds_read2_b32 v[6:7], v21 offset0:156 offset1:189
	v_addc_co_u32_e32 v11, vcc, 0, v11, vcc
	s_waitcnt lgkmcnt(0)
	v_cvt_pk_bf16_f32 v6, v6, v7
	ds_read2_b32 v[8:9], v21 offset0:222 offset1:255
	s_waitcnt lgkmcnt(0)
	v_cvt_pk_bf16_f32 v7, v8, v9
	global_store_dwordx4 v[10:11], v[4:7], off
	s_waitcnt lgkmcnt(0)
	v_readlane_b32 s40, v252, 11
	s_mov_b64 s[8:9], 0
	v_readlane_b32 s41, v252, 12
	v_readlane_b32 s42, v252, 13
	v_readlane_b32 s43, v252, 14
	v_readlane_b32 s44, v252, 15
	v_readlane_b32 s45, v252, 16
	v_readlane_b32 s46, v252, 17
	v_readlane_b32 s47, v252, 18

; #define LAS __attribute__((address_space(3)))
; __device__ __forceinline__ void transpose_item(const float* W, size_t ldw, bf16* WT, size_t K, LAS float* scr, int lane) {
; #pragma unroll 8
;     for (int i = 0; i < 32; ++i) { const int kk = 2 * i + (lane >> 5); scr[kk * 33 + (lane & 31)] = W[(size_t)kk * ldw + (lane & 31)]; }
;     asm volatile("s_waitcnt lgkmcnt(0)" ::: "memory");
.LBB0_48:
	s_lshl_b32 s25, s23, 1
	s_lshl_b32 s26, s7, 1
	v_or_b32_e32 v22, s25, v1
	v_or_b32_e32 v37, s26, v18
	s_add_i32 s28, s25, 4
	s_add_i32 s29, s26, 4
	s_add_i32 s30, s25, 8
	s_add_i32 s31, s26, 8
	s_add_i32 s33, s25, 12
	s_add_i32 s34, s26, 12
	s_add_i32 s35, s25, 16
	s_add_i32 s36, s26, 16
	s_add_i32 s37, s25, 20
	s_add_i32 s38, s26, 20
	s_add_i32 s39, s25, 24
	s_add_i32 s40, s26, 24
	s_add_i32 s25, s25, 28
	s_add_i32 s41, s26, 28
	v_mad_u64_u32 v[4:5], s[26:27], v37, s21, v[2:3]
	v_or_b32_e32 v39, s28, v1
	v_or_b32_e32 v41, s29, v18
	v_or_b32_e32 v43, s30, v1
	v_or_b32_e32 v45, s31, v18
	v_or_b32_e32 v49, s33, v1
	v_or_b32_e32 v66, s34, v18
	v_or_b32_e32 v67, s35, v1
	v_or_b32_e32 v68, s36, v18
	v_or_b32_e32 v69, s37, v1
	v_or_b32_e32 v70, s38, v18
	v_or_b32_e32 v71, s39, v1
	v_or_b32_e32 v72, s40, v18
	v_or_b32_e32 v73, s25, v1
	v_or_b32_e32 v74, s41, v18
	v_mad_u64_u32 v[6:7], s[26:27], v22, s21, v[2:3]
	v_mad_u64_u32 v[8:9], s[26:27], v41, s21, v[2:3]
	v_mad_u64_u32 v[10:11], s[26:27], v39, s21, v[2:3]
	v_mad_u64_u32 v[12:13], s[26:27], v45, s21, v[2:3]
	v_mad_u64_u32 v[14:15], s[26:27], v43, s21, v[2:3]
	v_mad_u64_u32 v[16:17], s[26:27], v66, s21, v[2:3]
	v_mad_u64_u32 v[46:47], s[26:27], v49, s21, v[2:3]
	v_mad_u64_u32 v[50:51], s[26:27], v68, s21, v[2:3]
	v_mad_u64_u32 v[52:53], s[26:27], v67, s21, v[2:3]
	v_mad_u64_u32 v[54:55], s[26:27], v70, s21, v[2:3]
	v_mad_u64_u32 v[56:57], s[26:27], v69, s21, v[2:3]
	v_mad_u64_u32 v[58:59], s[26:27], v72, s21, v[2:3]
	v_mad_u64_u32 v[60:61], s[26:27], v71, s21, v[2:3]
	v_mad_u64_u32 v[62:63], s[26:27], v74, s21, v[2:3]
	v_mad_u64_u32 v[64:65], s[26:27], v73, s21, v[2:3]
	global_load_dword v75, v[4:5], off
	global_load_dword v76, v[6:7], off
	global_load_dword v77, v[8:9], off
	global_load_dword v78, v[10:11], off
	global_load_dword v79, v[12:13], off
	global_load_dword v80, v[14:15], off
	global_load_dword v81, v[16:17], off
	global_load_dword v82, v[46:47], off
	global_load_dword v83, v[50:51], off
	global_load_dword v84, v[52:53], off
	global_load_dword v85, v[54:55], off
	global_load_dword v86, v[56:57], off
	global_load_dword v87, v[58:59], off
	global_load_dword v88, v[60:61], off
	global_load_dword v89, v[62:63], off
	global_load_dword v90, v[64:65], off
	s_add_i32 s7, s7, 16
	s_add_i32 s23, s23, 16
	s_add_i32 s11, s11, -16
	v_mad_u64_u32 v[4:5], s[26:27], v37, s14, v[24:25]
	s_cmp_lg_u32 s11, 0
	v_mad_u64_u32 v[6:7], s[26:27], v22, s14, v[24:25]
	v_mad_u64_u32 v[8:9], s[26:27], v41, s14, v[24:25]
	v_mad_u64_u32 v[10:11], s[26:27], v39, s14, v[24:25]
	v_mad_u64_u32 v[12:13], s[26:27], v45, s14, v[24:25]
	v_mad_u64_u32 v[14:15], s[26:27], v43, s14, v[24:25]
	v_mad_u64_u32 v[16:17], s[26:27], v66, s14, v[24:25]
	v_mad_u64_u32 v[46:47], s[26:27], v49, s14, v[24:25]
	v_mad_u64_u32 v[50:51], s[26:27], v68, s14, v[24:25]
	v_mad_u64_u32 v[52:53], s[26:27], v67, s14, v[24:25]
	v_mad_u64_u32 v[54:55], s[26:27], v70, s14, v[24:25]
	v_mad_u64_u32 v[56:57], s[26:27], v69, s14, v[24:25]
	v_mad_u64_u32 v[58:59], s[26:27], v72, s14, v[24:25]
	v_mad_u64_u32 v[60:61], s[26:27], v71, s14, v[24:25]
	v_mad_u64_u32 v[62:63], s[26:27], v74, s14, v[24:25]
	v_mad_u64_u32 v[64:65], s[26:27], v73, s14, v[24:25]
	s_lshl_b32 s25, s23, 1
	s_lshl_b32 s26, s7, 1
	v_or_b32_e32 v118, s25, v1
	v_or_b32_e32 v133, s26, v18
	s_add_i32 s28, s25, 4
	s_add_i32 s29, s26, 4
	s_add_i32 s30, s25, 8
	s_add_i32 s31, s26, 8
	s_add_i32 s33, s25, 12
	s_add_i32 s34, s26, 12
	s_add_i32 s35, s25, 16
	s_add_i32 s36, s26, 16
	s_add_i32 s37, s25, 20
	s_add_i32 s38, s26, 20
	s_add_i32 s39, s25, 24
	s_add_i32 s40, s26, 24
	s_add_i32 s25, s25, 28
	s_add_i32 s41, s26, 28
	v_mad_u64_u32 v[100:101], s[26:27], v133, s21, v[2:3]
	v_or_b32_e32 v135, s28, v1
	v_or_b32_e32 v137, s29, v18
	v_or_b32_e32 v139, s30, v1
	v_or_b32_e32 v141, s31, v18
	v_or_b32_e32 v145, s33, v1
	v_or_b32_e32 v162, s34, v18
	v_or_b32_e32 v163, s35, v1
	v_or_b32_e32 v164, s36, v18
	v_or_b32_e32 v165, s37, v1
	v_or_b32_e32 v166, s38, v18
	v_or_b32_e32 v167, s39, v1
	v_or_b32_e32 v168, s40, v18
	v_or_b32_e32 v169, s25, v1
	v_or_b32_e32 v170, s41, v18
	v_mad_u64_u32 v[102:103], s[26:27], v118, s21, v[2:3]
	v_mad_u64_u32 v[104:105], s[26:27], v137, s21, v[2:3]
	v_mad_u64_u32 v[106:107], s[26:27], v135, s21, v[2:3]
	v_mad_u64_u32 v[108:109], s[26:27], v141, s21, v[2:3]
	v_mad_u64_u32 v[110:111], s[26:27], v139, s21, v[2:3]
	v_mad_u64_u32 v[112:113], s[26:27], v162, s21, v[2:3]
	v_mad_u64_u32 v[142:143], s[26:27], v145, s21, v[2:3]
	v_mad_u64_u32 v[146:147], s[26:27], v164, s21, v[2:3]
	v_mad_u64_u32 v[148:149], s[26:27], v163, s21, v[2:3]
	v_mad_u64_u32 v[150:151], s[26:27], v166, s21, v[2:3]
	v_mad_u64_u32 v[152:153], s[26:27], v165, s21, v[2:3]
	v_mad_u64_u32 v[154:155], s[26:27], v168, s21, v[2:3]
	v_mad_u64_u32 v[156:157], s[26:27], v167, s21, v[2:3]
	v_mad_u64_u32 v[158:159], s[26:27], v170, s21, v[2:3]
	v_mad_u64_u32 v[160:161], s[26:27], v169, s21, v[2:3]
	global_load_dword v171, v[100:101], off
	global_load_dword v172, v[102:103], off
	global_load_dword v173, v[104:105], off
	global_load_dword v174, v[106:107], off
	global_load_dword v175, v[108:109], off
	global_load_dword v176, v[110:111], off
	global_load_dword v177, v[112:113], off
	global_load_dword v178, v[142:143], off
	global_load_dword v179, v[146:147], off
	global_load_dword v180, v[148:149], off
	global_load_dword v181, v[150:151], off
	global_load_dword v182, v[152:153], off
	global_load_dword v183, v[154:155], off
	global_load_dword v184, v[156:157], off
	global_load_dword v185, v[158:159], off
	global_load_dword v186, v[160:161], off
	s_add_i32 s7, s7, 16
	s_add_i32 s23, s23, 16
	s_add_i32 s11, s11, -16
	v_mad_u64_u32 v[100:101], s[26:27], v133, s14, v[24:25]
	s_cmp_lg_u32 s11, 0
	v_mad_u64_u32 v[102:103], s[26:27], v118, s14, v[24:25]
	v_mad_u64_u32 v[104:105], s[26:27], v137, s14, v[24:25]
	v_mad_u64_u32 v[106:107], s[26:27], v135, s14, v[24:25]
	v_mad_u64_u32 v[108:109], s[26:27], v141, s14, v[24:25]
	v_mad_u64_u32 v[110:111], s[26:27], v139, s14, v[24:25]
	v_mad_u64_u32 v[112:113], s[26:27], v162, s14, v[24:25]
	v_mad_u64_u32 v[142:143], s[26:27], v145, s14, v[24:25]
	v_mad_u64_u32 v[146:147], s[26:27], v164, s14, v[24:25]
	v_mad_u64_u32 v[148:149], s[26:27], v163, s14, v[24:25]
	v_mad_u64_u32 v[150:151], s[26:27], v166, s14, v[24:25]
	v_mad_u64_u32 v[152:153], s[26:27], v165, s14, v[24:25]
	v_mad_u64_u32 v[154:155], s[26:27], v168, s14, v[24:25]
	v_mad_u64_u32 v[156:157], s[26:27], v167, s14, v[24:25]
	v_mad_u64_u32 v[158:159], s[26:27], v170, s14, v[24:25]
	v_mad_u64_u32 v[160:161], s[26:27], v169, s14, v[24:25]
	s_waitcnt vmcnt(31)
; #define LAS __attribute__((address_space(3)))
; __device__ __forceinline__ unsigned cvt_pk_bf16(float lo, float hi) { unsigned r; asm volatile("v_cvt_pk_bf16_f32 %0, %1, %2" : "=v"(r) : "v"(lo), "v"(hi)); return r; }
; __device__ __forceinline__ void transpose_item(const float* W, size_t ldw, bf16* WT, size_t K, LAS float* scr, int lane) {
;     ...
;     for (int i = 0; i < 32; ++i) { const int kk = 2 * i + (lane >> 5); scr[kk * 33 + (lane & 31)] = W[(size_t)kk * ldw + (lane & 31)]; }
;     asm volatile("s_waitcnt lgkmcnt(0)" ::: "memory");
;     const int c = lane & 7;
; #pragma unroll
;     for (int j = 0; j < 4; ++j) { const int n = (lane >> 3) + 8 * j; const LAS float* s = scr + (8 * c) * 33 + n;
;         u32x4 o; o.x = cvt_pk_bf16(s[0 * 33], s[1 * 33]); o.y = cvt_pk_bf16(s[2 * 33], s[3 * 33]); o.z = cvt_pk_bf16(s[4 * 33], s[5 * 33]); o.w = cvt_pk_bf16(s[6 * 33], s[7 * 33]);
;         *(u32x4*)(WT + (size_t)n * K + 8 * c) = o; }
;     asm volatile("s_waitcnt lgkmcnt(0)" ::: "memory");
	ds_write_b32 v4, v75
	s_waitcnt vmcnt(30)
	ds_write_b32 v6, v76
	s_waitcnt vmcnt(29)
	ds_write_b32 v8, v77
	s_waitcnt vmcnt(28)
	ds_write_b32 v10, v78
	s_waitcnt vmcnt(27)
	ds_write_b32 v12, v79
	s_waitcnt vmcnt(26)
	ds_write_b32 v14, v80
	s_waitcnt vmcnt(25)
	ds_write_b32 v16, v81
	s_waitcnt vmcnt(24)
	ds_write_b32 v46, v82
	s_waitcnt vmcnt(23)
	ds_write_b32 v50, v83
	s_waitcnt vmcnt(22)
	ds_write_b32 v52, v84
	s_waitcnt vmcnt(21)
	ds_write_b32 v54, v85
	s_waitcnt vmcnt(20)
	ds_write_b32 v56, v86
	s_waitcnt vmcnt(19)
	ds_write_b32 v58, v87
	s_waitcnt vmcnt(18)
	ds_write_b32 v60, v88
	s_waitcnt vmcnt(17)
	ds_write_b32 v62, v89
	s_waitcnt vmcnt(16)
	ds_write_b32 v64, v90
	s_waitcnt vmcnt(15)
	ds_write_b32 v100, v171
	s_waitcnt vmcnt(14)
	ds_write_b32 v102, v172
	s_waitcnt vmcnt(13)
	ds_write_b32 v104, v173
	s_waitcnt vmcnt(12)
	ds_write_b32 v106, v174
	s_waitcnt vmcnt(11)
	ds_write_b32 v108, v175
	s_waitcnt vmcnt(10)
	ds_write_b32 v110, v176
	s_waitcnt vmcnt(9)
	ds_write_b32 v112, v177
	s_waitcnt vmcnt(8)
	ds_write_b32 v142, v178
	s_waitcnt vmcnt(7)
	ds_write_b32 v146, v179
	s_waitcnt vmcnt(6)
	ds_write_b32 v148, v180
	s_waitcnt vmcnt(5)
	ds_write_b32 v150, v181
	s_waitcnt vmcnt(4)
	ds_write_b32 v152, v182
	s_waitcnt vmcnt(3)
	ds_write_b32 v154, v183
	s_waitcnt vmcnt(2)
	ds_write_b32 v156, v184
	s_waitcnt vmcnt(1)
	ds_write_b32 v158, v185
	s_waitcnt vmcnt(0)
	ds_write_b32 v160, v186
	s_mul_hi_i32 s11, s6, 0x2c00000
	s_mul_i32 s23, s6, 0x2c00000
	s_lshl_b32 s6, s22, 6
	s_and_b32 s6, s6, 0xffffff00
	s_lshl_b32 s0, s0, 7
	s_add_i32 s6, s6, s0
	s_and_b32 s0, s10, 0x60
	s_or_b32 s6, s6, s0
	s_ashr_i32 s7, s6, 31
	s_lshl_b64 s[6:7], s[6:7], 12
	v_readlane_b32 s0, v252, 61
	s_add_u32 s0, s0, s23
	v_readlane_b32 s2, v252, 62
	s_addc_u32 s10, s2, s11
	s_add_u32 s0, s0, s6
	s_waitcnt lgkmcnt(0)
	s_addc_u32 s10, s10, s7
	s_lshl_b64 s[6:7], s[8:9], 1
	ds_read2_b32 v[2:3], v21 offset1:33
	s_add_u32 s6, s0, s6
	s_waitcnt lgkmcnt(0)
	v_cvt_pk_bf16_f32 v2, v2, v3
	ds_read2_b32 v[4:5], v21 offset0:66 offset1:99
	s_addc_u32 s7, s10, s7
	v_lshlrev_b32_e32 v22, 1, v26
	s_waitcnt lgkmcnt(0)
	v_cvt_pk_bf16_f32 v3, v4, v5
	ds_read2_b32 v[4:5], v21 offset0:132 offset1:165
	v_lshl_add_u64 v[8:9], s[6:7], 0, v[22:23]
	v_lshlrev_b32_e32 v22, 1, v28
	s_waitcnt lgkmcnt(0)
	v_cvt_pk_bf16_f32 v4, v4, v5
	ds_read2_b32 v[6:7], v21 offset0:198 offset1:231
	s_waitcnt lgkmcnt(0)
	v_cvt_pk_bf16_f32 v5, v6, v7
	v_lshl_add_u64 v[10:11], v[8:9], 0, v[22:23]
	ds_read2_b32 v[6:7], v21 offset0:8 offset1:41
	global_store_dwordx4 v[10:11], v[2:5], off
	v_lshlrev_b32_e32 v22, 1, v30
	v_lshl_add_u64 v[10:11], v[8:9], 0, v[22:23]
	s_waitcnt lgkmcnt(0)
	v_cvt_pk_bf16_f32 v2, v6, v7
	ds_read2_b32 v[4:5], v21 offset0:74 offset1:107
	s_waitcnt lgkmcnt(0)
	v_cvt_pk_bf16_f32 v3, v4, v5
	ds_read2_b32 v[4:5], v21 offset0:140 offset1:173
	s_waitcnt lgkmcnt(0)
	v_cvt_pk_bf16_f32 v4, v4, v5
	ds_read2_b32 v[6:7], v21 offset0:206 offset1:239
	s_waitcnt lgkmcnt(0)
	v_cvt_pk_bf16_f32 v5, v6, v7
	ds_read2_b32 v[6:7], v21 offset0:16 offset1:49
	global_store_dwordx4 v[10:11], v[2:5], off
	v_lshlrev_b32_e32 v22, 1, v32
	v_lshl_add_u64 v[10:11], v[8:9], 0, v[22:23]
	s_waitcnt lgkmcnt(0)
	v_cvt_pk_bf16_f32 v2, v6, v7
	ds_read2_b32 v[4:5], v21 offset0:82 offset1:115
	s_waitcnt lgkmcnt(0)
	v_cvt_pk_bf16_f32 v3, v4, v5
	ds_read2_b32 v[4:5], v21 offset0:148 offset1:181
	s_waitcnt lgkmcnt(0)
	v_cvt_pk_bf16_f32 v4, v4, v5
	ds_read2_b32 v[6:7], v21 offset0:214 offset1:247
	s_waitcnt lgkmcnt(0)
	v_cvt_pk_bf16_f32 v5, v6, v7
	ds_read2_b32 v[6:7], v21 offset0:24 offset1:57
	global_store_dwordx4 v[10:11], v[2:5], off
	v_lshlrev_b32_e32 v22, 1, v34
	v_readlane_b32 s40, v252, 11
	s_waitcnt lgkmcnt(0)
	v_cvt_pk_bf16_f32 v2, v6, v7
	ds_read2_b32 v[4:5], v21 offset0:90 offset1:123
	s_waitcnt lgkmcnt(0)
	v_cvt_pk_bf16_f32 v3, v4, v5
	ds_read2_b32 v[4:5], v21 offset0:156 offset1:189
	s_waitcnt lgkmcnt(0)
	v_cvt_pk_bf16_f32 v4, v4, v5
	ds_read2_b32 v[6:7], v21 offset0:222 offset1:255
	s_waitcnt lgkmcnt(0)
	v_cvt_pk_bf16_f32 v5, v6, v7
	v_lshl_add_u64 v[6:7], v[8:9], 0, v[22:23]
	global_store_dwordx4 v[6:7], v[2:5], off
	s_waitcnt lgkmcnt(0)
	v_readlane_b32 s41, v252, 12
	v_readlane_b32 s42, v252, 13
	v_readlane_b32 s43, v252, 14
	v_readlane_b32 s44, v252, 15
	v_readlane_b32 s45, v252, 16
	v_readlane_b32 s46, v252, 17
	v_readlane_b32 s47, v252, 18
	s_branch .LBB0_18
